# v9 + first K-iteration after an epilogue tolerates the epilogue stores in its first two load waits (counted vmcnt)
# baseline (speedup 1.0000x reference)
.LBB0_179:
	s_or_b64 exec, exec, s[6:7]
	s_cmpk_gt_i32 s2, 0xdff
	v_readfirstlane_b32 s18, v158
	s_barrier
	s_cbranch_scc1 .LBB0_217
	s_mov_b32 s32, 8
	v_lshrrev_b32_e32 v0, 5, v158
	v_lshrrev_b32_e32 v2, 1, v158
	v_and_b32_e32 v0, 4, v0
	v_bfe_u32 v1, v158, 2, 2
	v_and_b32_e32 v12, 24, v2
	v_add_u32_e32 v8, 0x2000, v74
	v_or3_b32 v0, v0, v1, v12
	v_lshrrev_b32_e32 v1, 7, v8
	s_movk_i32 s6, 0xe0
	v_and_b32_e32 v3, 32, v158
	s_lshr_b32 s7, s18, 6
	v_and_or_b32 v2, v1, s6, v0
	v_bitop3_b32 v9, v74, v3, 48 bitop3:0x6c
	v_and_b32_e32 v10, 64, v158
	v_bfe_u32 v11, v158, 2, 4
	s_movk_i32 s6, 0xf0
	s_lshr_b32 s16, s18, 8
	s_lshl_b32 s33, s7, 10
	v_or_b32_e32 v3, v9, v10
	v_and_or_b32 v1, v1, s6, v11
	s_add_u32 s60, s10, 0xd00000
	v_lshl_or_b32 v130, v1, 11, v3
	v_lshrrev_b32_e32 v1, 3, v158
	s_movk_i32 s6, 0x60
	s_addc_u32 s61, s11, 0
	v_and_or_b32 v0, v1, s6, v0
	s_movk_i32 s6, 0x70
	s_ashr_i32 s62, s2, 31
	v_lshl_or_b32 v132, v0, 11, v3
	v_and_or_b32 v0, v1, s6, v11
	s_lshr_b32 s6, s62, 29
	s_add_i32 s6, s2, s6
	s_ashr_i32 s14, s6, 3
	s_and_b32 s6, s6, -8
	s_sub_i32 s6, s2, s6
	s_cmp_lt_i32 s6, 0
	s_movk_i32 s63, 0x1c1
	s_cselect_b32 s15, s63, 0x1c0
	s_mul_i32 s6, s6, s15
	s_add_i32 s6, s6, s14
	s_mul_hi_i32 s14, s6, 0x92492493
	s_add_i32 s14, s14, s6
	s_lshr_b32 s15, s14, 31
	s_ashr_i32 s14, s14, 7
	s_add_i32 s14, s14, s15
	s_lshl_b32 s15, s14, 3
	s_mulk_i32 s14, 0xe0
	s_sub_i32 s14, s6, s14
	s_bfe_u32 s6, s14, 0x3001c
	s_add_i32 s17, s14, s6
	s_sext_i32_i16 s6, s17
	s_and_b32 s17, s17, 0xfff8
	s_sub_i32 s14, s14, s17
	s_sext_i32_i16 s14, s14
	s_lshr_b32 s6, s6, 3
	s_add_i32 s52, s15, s14
	s_ashr_i32 s53, s52, 31
	s_bfe_i64 s[20:21], s[6:7], 0x100000
	s_lshl_b64 s[14:15], s[52:53], 19
	s_lshl_b64 s[20:21], s[20:21], 19
	s_add_u32 s56, s60, s20
	s_addc_u32 s57, s61, s21
	s_add_i32 s64, s33, 0
	s_add_i32 m0, s64, 0x10000
	v_lshl_or_b32 v128, v2, 11, v3
	global_load_lds_dwordx4 v132, s[56:57]
	s_add_i32 m0, s64, 0x12000
	s_add_u32 s20, s56, 0x40000
	global_load_lds_dwordx4 v128, s[56:57]
	s_addc_u32 s21, s57, 0
	s_add_i32 m0, s64, 0x14000
	v_lshl_or_b32 v134, v0, 11, v3
	global_load_lds_dwordx4 v132, s[20:21]
	s_add_i32 m0, s64, 0x16000
	s_add_u32 s54, s8, s14
	s_addc_u32 s55, s9, s15
	s_add_i32 s65, s64, 0x2000
	global_load_lds_dwordx4 v128, s[20:21]
	s_mov_b32 m0, s64
	s_add_u32 s14, s54, 0x40000
	global_load_lds_dwordx4 v134, s[54:55]
	s_mov_b32 m0, s65
	s_addc_u32 s15, s55, 0
	s_add_i32 s66, s64, 0x4000
	global_load_lds_dwordx4 v130, s[54:55]
	s_mov_b32 m0, s66
	s_add_i32 s67, s64, 0x6000
	global_load_lds_dwordx4 v134, s[14:15]
	s_mov_b32 m0, s67
	v_mov_b32_e32 v137, 0
	global_load_lds_dwordx4 v130, s[14:15]
	v_mov_b32_e32 v133, v137
	v_mov_b32_e32 v129, v137
	v_mov_b32_e32 v135, v137
	v_mov_b32_e32 v131, v137
	s_cmp_eq_u32 s16, 1
	s_mov_b32 s68, 0
	v_lshl_add_u64 v[6:7], s[56:57], 0, v[132:133]
	v_lshl_add_u64 v[2:3], s[56:57], 0, v[128:129]
	v_lshl_add_u64 v[0:1], s[54:55], 0, v[134:135]
	s_cselect_b64 s[14:15], -1, 0
	s_cmp_lg_u32 s16, 1
	v_lshl_add_u64 v[4:5], s[54:55], 0, v[130:131]
	s_cbranch_scc1 .LBB0_182
	s_barrier

.LBB0_188:
	ds_read_b128 v[152:155], v160
	ds_read_b128 v[164:167], v160 offset:1024
	ds_read_b128 v[168:171], v160 offset:2048
	ds_read_b128 v[172:175], v160 offset:3072
	ds_read_b128 v[176:179], v161
	ds_read_b128 v[180:183], v161 offset:1024
	ds_read_b128 v[184:187], v161 offset:2048
	ds_read_b128 v[188:191], v161 offset:3072
	s_add_u32 s56, s54, 0xfffc0080
	s_addc_u32 s57, s55, -1
	s_cmp_eq_u32 s98, 12
	s_cselect_b32 s59, s47, s57
	s_cselect_b32 s58, s53, s56
	s_cselect_b32 s57, s45, s97
	s_cselect_b32 s56, s95, s96
	v_lshl_add_u64 v[156:157], s[54:55], 0, v[144:145]
	s_add_i32 m0, s64, 0xc000
	ds_read_b128 v[192:195], v162
	ds_read_b128 v[196:199], v162 offset:1024
	ds_read_b128 v[200:203], v162 offset:2048
	ds_read_b128 v[204:207], v162 offset:3072
	ds_read_b128 v[208:211], v162 offset:4096
	ds_read_b128 v[212:215], v162 offset:5120
	ds_read_b128 v[216:219], v162 offset:6144
	ds_read_b128 v[220:223], v162 offset:7168
	global_load_lds_dwordx4 v[156:157], off
	v_lshl_add_u64 v[156:157], s[54:55], 0, v[146:147]
	s_add_i32 m0, s64, 0xe000
	s_nop 0
	global_load_lds_dwordx4 v[156:157], off
	s_cmp_lt_u32 s32, 16
	s_cbranch_scc1 .Lrx_p1_0_8
	s_cmp_lt_u32 s32, 24
	s_cbranch_scc1 .Lrx_p1_0_16
	s_waitcnt vmcnt(24)
	s_branch .Lrx_p1_0_done
.Lrx_p1_0_16:
	s_waitcnt vmcnt(16)
	s_branch .Lrx_p1_0_done
.Lrx_p1_0_8:
	s_waitcnt vmcnt(8)
.Lrx_p1_0_done:
	s_waitcnt lgkmcnt(0)
	s_barrier
	s_setprio 1
	s_waitcnt lgkmcnt(0)
	v_mfma_f32_16x16x32_bf16 v[124:127], v[152:155], v[192:195], v[124:127]
	v_mfma_f32_16x16x32_bf16 v[120:123], v[168:171], v[192:195], v[120:123]
	v_mfma_f32_16x16x32_bf16 v[116:119], v[152:155], v[200:203], v[116:119]
	v_mfma_f32_16x16x32_bf16 v[112:115], v[168:171], v[200:203], v[112:115]
	v_mfma_f32_16x16x32_bf16 v[100:103], v[152:155], v[208:211], v[100:103]
	v_mfma_f32_16x16x32_bf16 v[96:99], v[168:171], v[208:211], v[96:99]
	v_mfma_f32_16x16x32_bf16 v[84:87], v[152:155], v[216:219], v[84:87]
	v_mfma_f32_16x16x32_bf16 v[80:83], v[168:171], v[216:219], v[80:83]
	v_mfma_f32_16x16x32_bf16 v[124:127], v[164:167], v[196:199], v[124:127]
	v_mfma_f32_16x16x32_bf16 v[120:123], v[172:175], v[196:199], v[120:123]
	v_mfma_f32_16x16x32_bf16 v[116:119], v[164:167], v[204:207], v[116:119]
	v_mfma_f32_16x16x32_bf16 v[112:115], v[172:175], v[204:207], v[112:115]
	v_mfma_f32_16x16x32_bf16 v[100:103], v[164:167], v[212:215], v[100:103]
	v_mfma_f32_16x16x32_bf16 v[96:99], v[172:175], v[212:215], v[96:99]
	v_mfma_f32_16x16x32_bf16 v[84:87], v[164:167], v[220:223], v[84:87]
	v_mfma_f32_16x16x32_bf16 v[80:83], v[172:175], v[220:223], v[80:83]
	s_setprio 0
	s_setprio 1
	v_mfma_f32_16x16x32_bf16 v[108:111], v[176:179], v[192:195], v[108:111]
	v_mfma_f32_16x16x32_bf16 v[104:107], v[184:187], v[192:195], v[104:107]
	v_mfma_f32_16x16x32_bf16 v[92:95], v[176:179], v[200:203], v[92:95]
	v_mfma_f32_16x16x32_bf16 v[88:91], v[184:187], v[200:203], v[88:91]
	v_mfma_f32_16x16x32_bf16 v[76:79], v[176:179], v[208:211], v[76:79]
	v_mfma_f32_16x16x32_bf16 v[72:75], v[184:187], v[208:211], v[72:75]
	v_mfma_f32_16x16x32_bf16 v[68:71], v[176:179], v[216:219], v[68:71]
	v_mfma_f32_16x16x32_bf16 v[64:67], v[184:187], v[216:219], v[64:67]
	v_mfma_f32_16x16x32_bf16 v[108:111], v[180:183], v[196:199], v[108:111]
	v_mfma_f32_16x16x32_bf16 v[104:107], v[188:191], v[196:199], v[104:107]
	v_mfma_f32_16x16x32_bf16 v[92:95], v[180:183], v[204:207], v[92:95]
	v_mfma_f32_16x16x32_bf16 v[88:91], v[188:191], v[204:207], v[88:91]
	v_mfma_f32_16x16x32_bf16 v[76:79], v[180:183], v[212:215], v[76:79]
	v_mfma_f32_16x16x32_bf16 v[72:75], v[188:191], v[212:215], v[72:75]
	v_mfma_f32_16x16x32_bf16 v[68:71], v[180:183], v[220:223], v[68:71]
	v_mfma_f32_16x16x32_bf16 v[64:67], v[188:191], v[220:223], v[64:67]
	s_setprio 0
	s_barrier
	s_add_i32 s99, s74, s33
	v_lshl_add_u64 v[156:157], s[56:57], 0, v[132:133]
	s_mov_b32 m0, s99
	ds_read_b128 v[192:195], v162 offset:16384
	ds_read_b128 v[196:199], v162 offset:17408
	ds_read_b128 v[200:203], v162 offset:18432
	ds_read_b128 v[204:207], v162 offset:19456
	ds_read_b128 v[208:211], v162 offset:20480
	ds_read_b128 v[212:215], v162 offset:21504
	ds_read_b128 v[216:219], v162 offset:22528
	ds_read_b128 v[220:223], v162 offset:23552
	global_load_lds_dwordx4 v[156:157], off
	s_add_i32 m0, s99, 0x2000
	s_add_u32 vcc_lo, s56, 0x40000
	v_lshl_add_u64 v[224:225], s[56:57], 0, v[128:129]
	s_addc_u32 vcc_hi, s57, 0
	s_add_i32 s99, s75, s33
	global_load_lds_dwordx4 v[224:225], off
	v_lshl_add_u64 v[226:227], vcc, 0, v[132:133]
	s_mov_b32 m0, s99
	v_lshl_add_u64 v[228:229], s[58:59], 0, v[130:131]
	global_load_lds_dwordx4 v[226:227], off
	v_lshl_add_u64 v[226:227], vcc, 0, v[128:129]
	s_add_i32 m0, s99, 0x2000
	s_nop 0
	global_load_lds_dwordx4 v[226:227], off
	v_lshl_add_u64 v[226:227], s[58:59], 0, v[134:135]
	s_mov_b32 m0, s64
	s_nop 0
	global_load_lds_dwordx4 v[226:227], off
	s_mov_b32 m0, s65
	s_nop 0
	global_load_lds_dwordx4 v[228:229], off
	s_cmp_lt_u32 s32, 16
	s_cbranch_scc1 .Lrx_p1_1_8
	s_cmp_lt_u32 s32, 24
	s_cbranch_scc1 .Lrx_p1_1_16
	s_waitcnt vmcnt(24)
	s_branch .Lrx_p1_1_done

.Lrx_p1_1_done:
	s_mov_b32 s32, 8
	s_waitcnt lgkmcnt(0)
	s_barrier
	s_setprio 1
	s_waitcnt lgkmcnt(0)
	v_mfma_f32_16x16x32_bf16 v[60:63], v[152:155], v[192:195], v[60:63]
	v_mfma_f32_16x16x32_bf16 v[56:59], v[168:171], v[192:195], v[56:59]
	v_mfma_f32_16x16x32_bf16 v[52:55], v[152:155], v[200:203], v[52:55]
	v_mfma_f32_16x16x32_bf16 v[48:51], v[168:171], v[200:203], v[48:51]
	v_mfma_f32_16x16x32_bf16 v[36:39], v[152:155], v[208:211], v[36:39]
	v_mfma_f32_16x16x32_bf16 v[32:35], v[168:171], v[208:211], v[32:35]
	v_mfma_f32_16x16x32_bf16 v[20:23], v[152:155], v[216:219], v[20:23]
	v_mfma_f32_16x16x32_bf16 v[16:19], v[168:171], v[216:219], v[16:19]
	v_mfma_f32_16x16x32_bf16 v[60:63], v[164:167], v[196:199], v[60:63]
	v_mfma_f32_16x16x32_bf16 v[56:59], v[172:175], v[196:199], v[56:59]
	v_mfma_f32_16x16x32_bf16 v[52:55], v[164:167], v[204:207], v[52:55]
	v_mfma_f32_16x16x32_bf16 v[48:51], v[172:175], v[204:207], v[48:51]
	v_mfma_f32_16x16x32_bf16 v[36:39], v[164:167], v[212:215], v[36:39]
	v_mfma_f32_16x16x32_bf16 v[32:35], v[172:175], v[212:215], v[32:35]
	v_mfma_f32_16x16x32_bf16 v[20:23], v[164:167], v[220:223], v[20:23]
	v_mfma_f32_16x16x32_bf16 v[16:19], v[172:175], v[220:223], v[16:19]
	s_setprio 0
	s_setprio 1
	v_mfma_f32_16x16x32_bf16 v[44:47], v[176:179], v[192:195], v[44:47]
	v_mfma_f32_16x16x32_bf16 v[40:43], v[184:187], v[192:195], v[40:43]
	v_mfma_f32_16x16x32_bf16 v[28:31], v[176:179], v[200:203], v[28:31]
	v_mfma_f32_16x16x32_bf16 v[24:27], v[184:187], v[200:203], v[24:27]
	v_mfma_f32_16x16x32_bf16 v[12:15], v[176:179], v[208:211], v[12:15]
	v_mfma_f32_16x16x32_bf16 v[8:11], v[184:187], v[208:211], v[8:11]
	v_mfma_f32_16x16x32_bf16 v[4:7], v[176:179], v[216:219], v[4:7]
	v_mfma_f32_16x16x32_bf16 v[0:3], v[184:187], v[216:219], v[0:3]
	v_mfma_f32_16x16x32_bf16 v[44:47], v[180:183], v[196:199], v[44:47]
	v_mfma_f32_16x16x32_bf16 v[40:43], v[188:191], v[196:199], v[40:43]
	v_mfma_f32_16x16x32_bf16 v[28:31], v[180:183], v[204:207], v[28:31]
	v_mfma_f32_16x16x32_bf16 v[24:27], v[188:191], v[204:207], v[24:27]
	v_mfma_f32_16x16x32_bf16 v[12:15], v[180:183], v[212:215], v[12:15]
	v_mfma_f32_16x16x32_bf16 v[8:11], v[188:191], v[212:215], v[8:11]
	v_mfma_f32_16x16x32_bf16 v[4:7], v[180:183], v[220:223], v[4:7]
	v_mfma_f32_16x16x32_bf16 v[0:3], v[188:191], v[220:223], v[0:3]
	s_setprio 0
	s_barrier
	s_add_i32 s99, 0, 0x18000
	v_add_u32_e32 v136, s99, v159
	s_add_i32 vcc_lo, 0, 0x1c000
	ds_read_b128 v[152:155], v136
	ds_read_b128 v[164:167], v136 offset:1024
	ds_read_b128 v[168:171], v136 offset:2048
	ds_read_b128 v[172:175], v136 offset:3072
	v_add_u32_e32 v136, vcc_lo, v159
	ds_read_b128 v[176:179], v136
	ds_read_b128 v[180:183], v136 offset:1024
	ds_read_b128 v[184:187], v136 offset:2048
	ds_read_b128 v[188:191], v136 offset:3072
	s_add_u32 s58, s58, 0x40000
	s_addc_u32 s59, s59, 0
	s_mov_b32 m0, s66
	v_lshl_add_u64 v[230:231], s[58:59], 0, v[134:135]
	ds_read_b128 v[192:195], v162 offset:32768
	ds_read_b128 v[196:199], v162 offset:33792
	ds_read_b128 v[200:203], v162 offset:34816
	ds_read_b128 v[204:207], v162 offset:35840
	ds_read_b128 v[208:211], v162 offset:36864
	ds_read_b128 v[212:215], v162 offset:37888
	ds_read_b128 v[216:219], v162 offset:38912
	ds_read_b128 v[220:223], v162 offset:39936
	global_load_lds_dwordx4 v[230:231], off
	v_lshl_add_u64 v[230:231], s[58:59], 0, v[130:131]
	s_mov_b32 m0, s67
	s_nop 0
	global_load_lds_dwordx4 v[230:231], off
	s_waitcnt vmcnt(8)
	s_waitcnt lgkmcnt(0)
	s_barrier
	s_setprio 1
	s_waitcnt lgkmcnt(0)
	v_mfma_f32_16x16x32_bf16 v[124:127], v[152:155], v[192:195], v[124:127]
	v_mfma_f32_16x16x32_bf16 v[120:123], v[168:171], v[192:195], v[120:123]
	v_mfma_f32_16x16x32_bf16 v[116:119], v[152:155], v[200:203], v[116:119]
	v_mfma_f32_16x16x32_bf16 v[112:115], v[168:171], v[200:203], v[112:115]
	v_mfma_f32_16x16x32_bf16 v[100:103], v[152:155], v[208:211], v[100:103]
	v_mfma_f32_16x16x32_bf16 v[96:99], v[168:171], v[208:211], v[96:99]
	v_mfma_f32_16x16x32_bf16 v[84:87], v[152:155], v[216:219], v[84:87]
	v_mfma_f32_16x16x32_bf16 v[80:83], v[168:171], v[216:219], v[80:83]
	v_mfma_f32_16x16x32_bf16 v[124:127], v[164:167], v[196:199], v[124:127]
	v_mfma_f32_16x16x32_bf16 v[120:123], v[172:175], v[196:199], v[120:123]
	v_mfma_f32_16x16x32_bf16 v[116:119], v[164:167], v[204:207], v[116:119]
	v_mfma_f32_16x16x32_bf16 v[112:115], v[172:175], v[204:207], v[112:115]
	v_mfma_f32_16x16x32_bf16 v[100:103], v[164:167], v[212:215], v[100:103]
	v_mfma_f32_16x16x32_bf16 v[96:99], v[172:175], v[212:215], v[96:99]
	v_mfma_f32_16x16x32_bf16 v[84:87], v[164:167], v[220:223], v[84:87]
	v_mfma_f32_16x16x32_bf16 v[80:83], v[172:175], v[220:223], v[80:83]
	s_setprio 0
	s_setprio 1
	v_mfma_f32_16x16x32_bf16 v[108:111], v[176:179], v[192:195], v[108:111]
	v_mfma_f32_16x16x32_bf16 v[104:107], v[184:187], v[192:195], v[104:107]
	v_mfma_f32_16x16x32_bf16 v[92:95], v[176:179], v[200:203], v[92:95]
	v_mfma_f32_16x16x32_bf16 v[88:91], v[184:187], v[200:203], v[88:91]
	v_mfma_f32_16x16x32_bf16 v[76:79], v[176:179], v[208:211], v[76:79]
	v_mfma_f32_16x16x32_bf16 v[72:75], v[184:187], v[208:211], v[72:75]
	v_mfma_f32_16x16x32_bf16 v[68:71], v[176:179], v[216:219], v[68:71]
	v_mfma_f32_16x16x32_bf16 v[64:67], v[184:187], v[216:219], v[64:67]
	v_mfma_f32_16x16x32_bf16 v[108:111], v[180:183], v[196:199], v[108:111]
	v_mfma_f32_16x16x32_bf16 v[104:107], v[188:191], v[196:199], v[104:107]
	v_mfma_f32_16x16x32_bf16 v[92:95], v[180:183], v[204:207], v[92:95]
	v_mfma_f32_16x16x32_bf16 v[88:91], v[188:191], v[204:207], v[88:91]
	v_mfma_f32_16x16x32_bf16 v[76:79], v[180:183], v[212:215], v[76:79]
	v_mfma_f32_16x16x32_bf16 v[72:75], v[188:191], v[212:215], v[72:75]
	v_mfma_f32_16x16x32_bf16 v[68:71], v[180:183], v[220:223], v[68:71]
	v_mfma_f32_16x16x32_bf16 v[64:67], v[188:191], v[220:223], v[64:67]
	s_setprio 0
	s_barrier
	s_add_i32 s58, s99, s33
	v_lshl_add_u64 v[156:157], v[156:157], 0, s[16:17]
	s_mov_b32 m0, s58
	ds_read_b128 v[192:195], v162 offset:49152
	ds_read_b128 v[196:199], v162 offset:50176
	ds_read_b128 v[200:203], v162 offset:51200
	ds_read_b128 v[204:207], v162 offset:52224
	ds_read_b128 v[208:211], v162 offset:53248
	ds_read_b128 v[212:215], v162 offset:54272
	ds_read_b128 v[216:219], v162 offset:55296
	ds_read_b128 v[220:223], v162 offset:56320
	global_load_lds_dwordx4 v[156:157], off
	s_add_i32 m0, s58, 0x2000
	s_add_u32 s56, s56, 0x40080
	v_lshl_add_u64 v[156:157], v[224:225], 0, s[16:17]
	s_addc_u32 s57, s57, 0
	s_add_i32 s58, vcc_lo, s33
	global_load_lds_dwordx4 v[156:157], off
	v_lshl_add_u64 v[156:157], s[56:57], 0, v[132:133]
	s_mov_b32 m0, s58
	s_nop 0
	global_load_lds_dwordx4 v[156:157], off
	v_lshl_add_u64 v[156:157], s[56:57], 0, v[128:129]
	s_add_i32 m0, s58, 0x2000
	s_nop 0
	global_load_lds_dwordx4 v[156:157], off
	v_lshl_add_u64 v[156:157], v[226:227], 0, s[16:17]
	s_mov_b32 m0, s70
	s_nop 0
	global_load_lds_dwordx4 v[156:157], off
	v_lshl_add_u64 v[156:157], v[228:229], 0, s[16:17]
	s_mov_b32 m0, s71
	s_nop 0
	global_load_lds_dwordx4 v[156:157], off
	s_waitcnt vmcnt(8)
	s_waitcnt lgkmcnt(0)
	s_barrier
	s_setprio 1
	s_waitcnt lgkmcnt(0)
	v_mfma_f32_16x16x32_bf16 v[60:63], v[152:155], v[192:195], v[60:63]
	v_mfma_f32_16x16x32_bf16 v[56:59], v[168:171], v[192:195], v[56:59]
	v_mfma_f32_16x16x32_bf16 v[52:55], v[152:155], v[200:203], v[52:55]
	v_mfma_f32_16x16x32_bf16 v[48:51], v[168:171], v[200:203], v[48:51]
	v_mfma_f32_16x16x32_bf16 v[36:39], v[152:155], v[208:211], v[36:39]
	v_mfma_f32_16x16x32_bf16 v[32:35], v[168:171], v[208:211], v[32:35]
	v_mfma_f32_16x16x32_bf16 v[20:23], v[152:155], v[216:219], v[20:23]
	v_mfma_f32_16x16x32_bf16 v[16:19], v[168:171], v[216:219], v[16:19]
	v_mfma_f32_16x16x32_bf16 v[60:63], v[164:167], v[196:199], v[60:63]
	v_mfma_f32_16x16x32_bf16 v[56:59], v[172:175], v[196:199], v[56:59]
	v_mfma_f32_16x16x32_bf16 v[52:55], v[164:167], v[204:207], v[52:55]
	v_mfma_f32_16x16x32_bf16 v[48:51], v[172:175], v[204:207], v[48:51]
	v_mfma_f32_16x16x32_bf16 v[36:39], v[164:167], v[212:215], v[36:39]
	v_mfma_f32_16x16x32_bf16 v[32:35], v[172:175], v[212:215], v[32:35]
	v_mfma_f32_16x16x32_bf16 v[20:23], v[164:167], v[220:223], v[20:23]
	v_mfma_f32_16x16x32_bf16 v[16:19], v[172:175], v[220:223], v[16:19]
	s_setprio 0
	s_setprio 1
	v_mfma_f32_16x16x32_bf16 v[44:47], v[176:179], v[192:195], v[44:47]
	v_mfma_f32_16x16x32_bf16 v[40:43], v[184:187], v[192:195], v[40:43]
	v_mfma_f32_16x16x32_bf16 v[28:31], v[176:179], v[200:203], v[28:31]
	v_mfma_f32_16x16x32_bf16 v[24:27], v[184:187], v[200:203], v[24:27]
	v_mfma_f32_16x16x32_bf16 v[12:15], v[176:179], v[208:211], v[12:15]
	v_mfma_f32_16x16x32_bf16 v[8:11], v[184:187], v[208:211], v[8:11]
	v_mfma_f32_16x16x32_bf16 v[4:7], v[176:179], v[216:219], v[4:7]
	v_mfma_f32_16x16x32_bf16 v[0:3], v[184:187], v[216:219], v[0:3]
	v_mfma_f32_16x16x32_bf16 v[44:47], v[180:183], v[196:199], v[44:47]
	v_mfma_f32_16x16x32_bf16 v[40:43], v[188:191], v[196:199], v[40:43]
	v_mfma_f32_16x16x32_bf16 v[28:31], v[180:183], v[204:207], v[28:31]
	v_mfma_f32_16x16x32_bf16 v[24:27], v[188:191], v[204:207], v[24:27]
	v_mfma_f32_16x16x32_bf16 v[12:15], v[180:183], v[212:215], v[12:15]
	v_mfma_f32_16x16x32_bf16 v[8:11], v[188:191], v[212:215], v[8:11]
	v_mfma_f32_16x16x32_bf16 v[4:7], v[180:183], v[220:223], v[4:7]
	v_mfma_f32_16x16x32_bf16 v[0:3], v[188:191], v[220:223], v[0:3]
	s_setprio 0
	s_barrier
	s_add_i32 s98, s98, 2
	s_add_u32 s54, s54, 0x100
	s_addc_u32 s55, s55, 0
	s_add_u32 s96, s96, 0x100
	s_addc_u32 s97, s97, 0
	s_cmp_gt_u32 s98, 13
	s_cbranch_scc0 .LBB0_188
	s_and_b64 vcc, exec, s[18:19]
	s_cbranch_vccz .LBB0_191
	s_barrier

.LBB0_194:
	s_cmp_gt_i32 s94, 3
	s_cbranch_scc0 .LBB0_210
	s_cmp_gt_u32 s94, 11
	s_cbranch_scc0 .LBB0_207
	s_cmp_gt_u32 s94, 19
	s_cbranch_scc0 .LBB0_204
	s_cmp_gt_u32 s94, 27
	s_cbranch_scc0 .LBB0_201
	s_andn2_b64 vcc, exec, s[20:21]
	s_cbranch_vccnz .LBB0_200
	s_mov_b32 s32, 24
	v_or_b32_e32 v156, 16, v152
	v_ashrrev_i32_e32 v153, 31, v152
	v_ashrrev_i32_e32 v157, 31, v156
	v_lshlrev_b64 v[154:155], 7, v[152:153]
	v_lshlrev_b64 v[156:157], 7, v[156:157]
	v_lshl_add_u64 v[154:155], v[140:141], 0, v[154:155]
	v_lshl_add_u64 v[156:157], v[140:141], 0, v[156:157]
	global_store_dwordx4 v[154:155], v[124:127], off
	global_store_dwordx4 v[154:155], v[120:123], off offset:16
	global_store_dwordx4 v[156:157], v[116:119], off
	global_store_dwordx4 v[156:157], v[112:115], off offset:16
	v_or_b32_e32 v156, 32, v152
	v_ashrrev_i32_e32 v157, 31, v156
	v_lshlrev_b64 v[156:157], 7, v[156:157]
	v_lshl_add_u64 v[156:157], v[140:141], 0, v[156:157]
	global_store_dwordx4 v[156:157], v[100:103], off
	global_store_dwordx4 v[156:157], v[96:99], off offset:16
	v_or_b32_e32 v156, 48, v152
	v_ashrrev_i32_e32 v157, 31, v156
	v_lshlrev_b64 v[156:157], 7, v[156:157]
	s_movk_i32 s47, 0x4000
	v_lshl_add_u64 v[156:157], v[140:141], 0, v[156:157]
	s_mov_b64 s[52:53], 0x4000
	v_add_co_u32_e32 v164, vcc, s47, v154
	global_store_dwordx4 v[156:157], v[84:87], off
	global_store_dwordx4 v[156:157], v[80:83], off offset:16
	v_lshl_add_u64 v[156:157], v[154:155], 0, s[52:53]
	v_addc_co_u32_e32 v165, vcc, 0, v155, vcc
	s_mov_b64 s[52:53], 0x4800
	global_store_dwordx4 v[164:165], v[60:63], off
	global_store_dwordx4 v[156:157], v[56:59], off offset:16
	v_lshl_add_u64 v[156:157], v[154:155], 0, s[52:53]
	global_store_dwordx4 v[164:165], v[52:55], off offset:2048
	global_store_dwordx4 v[156:157], v[48:51], off offset:16
	s_mov_b64 s[52:53], 0x5000
	v_add_co_u32_e32 v164, vcc, 0x5000, v154
	v_lshl_add_u64 v[156:157], v[154:155], 0, s[52:53]
	s_nop 0
	v_addc_co_u32_e32 v165, vcc, 0, v155, vcc
	s_mov_b64 s[52:53], 0x5800
	global_store_dwordx4 v[164:165], v[36:39], off
	global_store_dwordx4 v[156:157], v[32:35], off offset:16
	v_lshl_add_u64 v[154:155], v[154:155], 0, s[52:53]
	global_store_dwordx4 v[164:165], v[20:23], off offset:2048
	global_store_dwordx4 v[154:155], v[16:19], off offset:16

.LBB0_201:
	s_andn2_b64 vcc, exec, s[52:53]
	s_cbranch_vccnz .LBB0_203
	s_mov_b32 s32, 16
	v_ashrrev_i32_e32 v153, 31, v152
	v_mul_f32_e32 v136, 0xbfb8aa3b, v108
	v_lshlrev_b64 v[154:155], 11, v[152:153]
	v_exp_f32_e32 v153, v136
	v_mul_f32_e32 v136, 0xbfb8aa3b, v109
	v_exp_f32_e32 v157, v136
	s_lshl_b32 s47, s94, 8
	v_add_f32_e32 v153, 1.0, v153
	v_rcp_f32_e32 v156, v153
	v_add_f32_e32 v153, 1.0, v157
	v_mul_f32_e32 v157, 0xbfb8aa3b, v110
	v_exp_f32_e32 v164, v157
	v_mul_f32_e32 v157, 0xbfb8aa3b, v111
	v_exp_f32_e32 v165, v157
	v_rcp_f32_e32 v157, v153
	v_add_f32_e32 v153, 1.0, v164
	v_rcp_f32_e32 v166, v153
	v_add_f32_e32 v153, 1.0, v165
	v_rcp_f32_e32 v167, v153
	v_pk_mul_f32 v[156:157], v[108:109], v[156:157]
	v_mul_f32_e32 v153, 0xbfb8aa3b, v104
	v_pk_mul_f32 v[156:157], v[124:125], v[156:157]
	v_exp_f32_e32 v153, v153
	v_mul_f32_e32 v165, 0xbfb8aa3b, v105
	v_cvt_pk_bf16_f32 v164, v156, v157
	v_pk_mul_f32 v[156:157], v[110:111], v[166:167]
	v_exp_f32_e32 v166, v165
	v_pk_mul_f32 v[156:157], v[126:127], v[156:157]
	v_add_f32_e32 v153, 1.0, v153
	v_cvt_pk_bf16_f32 v165, v156, v157
	v_mul_f32_e32 v157, 0xbfb8aa3b, v106
	v_rcp_f32_e32 v156, v153
	v_add_f32_e32 v153, 1.0, v166
	v_exp_f32_e32 v166, v157
	v_mul_f32_e32 v157, 0xbfb8aa3b, v107
	v_exp_f32_e32 v167, v157
	v_rcp_f32_e32 v157, v153
	v_add_f32_e32 v153, 1.0, v166
	v_rcp_f32_e32 v168, v153
	v_add_f32_e32 v153, 1.0, v167
	v_rcp_f32_e32 v169, v153
	s_add_u32 s52, s10, s47
	v_pk_mul_f32 v[156:157], v[104:105], v[156:157]
	s_addc_u32 s53, s11, 0
	v_pk_mul_f32 v[156:157], v[120:121], v[156:157]
	v_lshl_add_u64 v[154:155], s[52:53], 0, v[154:155]
	v_lshlrev_b32_e32 v136, 1, v138
	v_cvt_pk_bf16_f32 v166, v156, v157
	v_pk_mul_f32 v[156:157], v[106:107], v[168:169]
	v_lshl_add_u64 v[154:155], v[154:155], 0, v[136:137]
	v_pk_mul_f32 v[156:157], v[122:123], v[156:157]
	v_mul_f32_e32 v153, 0xbfb8aa3b, v92
	v_cvt_pk_bf16_f32 v167, v156, v157
	v_add_co_u32_e32 v156, vcc, s76, v154
	v_exp_f32_e32 v153, v153
	s_nop 0
	v_addc_co_u32_e32 v157, vcc, 0, v155, vcc
	global_store_dwordx4 v[156:157], v[164:167], off offset:3072 nt
	v_add_f32_e32 v153, 1.0, v153
	v_or_b32_e32 v156, 16, v152
	v_mul_f32_e32 v164, 0xbfb8aa3b, v93
	v_exp_f32_e32 v165, v164
	v_rcp_f32_e32 v164, v153
	v_ashrrev_i32_e32 v157, 31, v156
	v_lshlrev_b64 v[156:157], 11, v[156:157]
	v_add_f32_e32 v153, 1.0, v165
	v_mul_f32_e32 v165, 0xbfb8aa3b, v94
	v_exp_f32_e32 v166, v165
	v_mul_f32_e32 v165, 0xbfb8aa3b, v95
	v_exp_f32_e32 v167, v165
	v_rcp_f32_e32 v165, v153
	v_add_f32_e32 v153, 1.0, v166
	v_rcp_f32_e32 v166, v153
	v_add_f32_e32 v153, 1.0, v167
	v_rcp_f32_e32 v167, v153
	v_pk_mul_f32 v[164:165], v[92:93], v[164:165]
	v_mul_f32_e32 v153, 0xbfb8aa3b, v88
	v_pk_mul_f32 v[164:165], v[116:117], v[164:165]
	v_exp_f32_e32 v153, v153
	v_cvt_pk_bf16_f32 v164, v164, v165
	v_mul_f32_e32 v165, 0xbfb8aa3b, v89
	v_exp_f32_e32 v168, v165
	v_pk_mul_f32 v[166:167], v[94:95], v[166:167]
	v_add_f32_e32 v153, 1.0, v153
	v_pk_mul_f32 v[166:167], v[118:119], v[166:167]
	v_lshl_add_u64 v[156:157], s[52:53], 0, v[156:157]
	v_cvt_pk_bf16_f32 v165, v166, v167
	v_mul_f32_e32 v167, 0xbfb8aa3b, v90
	v_rcp_f32_e32 v166, v153
	v_add_f32_e32 v153, 1.0, v168
	v_exp_f32_e32 v168, v167
	v_mul_f32_e32 v167, 0xbfb8aa3b, v91
	v_exp_f32_e32 v169, v167
	v_rcp_f32_e32 v167, v153
	v_add_f32_e32 v153, 1.0, v168
	v_rcp_f32_e32 v168, v153
	v_add_f32_e32 v153, 1.0, v169
	v_rcp_f32_e32 v169, v153
	v_lshl_add_u64 v[156:157], v[156:157], 0, v[136:137]
	v_pk_mul_f32 v[166:167], v[88:89], v[166:167]
	v_add_co_u32_e32 v156, vcc, s76, v156
	v_pk_mul_f32 v[168:169], v[90:91], v[168:169]
	v_pk_mul_f32 v[166:167], v[112:113], v[166:167]
	v_pk_mul_f32 v[168:169], v[114:115], v[168:169]
	v_cvt_pk_bf16_f32 v166, v166, v167
	v_cvt_pk_bf16_f32 v167, v168, v169
	v_addc_co_u32_e32 v157, vcc, 0, v157, vcc
	v_mul_f32_e32 v153, 0xbfb8aa3b, v76
	global_store_dwordx4 v[156:157], v[164:167], off offset:3072 nt
	v_exp_f32_e32 v153, v153
	v_or_b32_e32 v156, 32, v152
	v_mul_f32_e32 v164, 0xbfb8aa3b, v77
	v_exp_f32_e32 v165, v164
	v_add_f32_e32 v153, 1.0, v153
	v_rcp_f32_e32 v164, v153
	v_ashrrev_i32_e32 v157, 31, v156
	v_add_f32_e32 v153, 1.0, v165
	v_mul_f32_e32 v165, 0xbfb8aa3b, v78
	v_exp_f32_e32 v166, v165
	v_mul_f32_e32 v165, 0xbfb8aa3b, v79
	v_exp_f32_e32 v167, v165
	v_rcp_f32_e32 v165, v153
	v_add_f32_e32 v153, 1.0, v166
	v_rcp_f32_e32 v166, v153
	v_add_f32_e32 v153, 1.0, v167
	v_rcp_f32_e32 v167, v153
	v_pk_mul_f32 v[164:165], v[76:77], v[164:165]
	v_mul_f32_e32 v153, 0xbfb8aa3b, v72
	v_pk_mul_f32 v[164:165], v[100:101], v[164:165]
	v_exp_f32_e32 v153, v153
	v_cvt_pk_bf16_f32 v164, v164, v165
	v_mul_f32_e32 v165, 0xbfb8aa3b, v73
	v_exp_f32_e32 v168, v165
	v_pk_mul_f32 v[166:167], v[78:79], v[166:167]
	v_add_f32_e32 v153, 1.0, v153
	v_pk_mul_f32 v[166:167], v[102:103], v[166:167]
	v_lshlrev_b64 v[156:157], 11, v[156:157]
	v_cvt_pk_bf16_f32 v165, v166, v167
	v_mul_f32_e32 v167, 0xbfb8aa3b, v74
	v_rcp_f32_e32 v166, v153
	v_add_f32_e32 v153, 1.0, v168
	v_exp_f32_e32 v168, v167
	v_mul_f32_e32 v167, 0xbfb8aa3b, v75
	v_exp_f32_e32 v169, v167
	v_rcp_f32_e32 v167, v153
	v_add_f32_e32 v153, 1.0, v168
	v_rcp_f32_e32 v168, v153
	v_add_f32_e32 v153, 1.0, v169
	v_rcp_f32_e32 v169, v153
	v_lshl_add_u64 v[156:157], s[52:53], 0, v[156:157]
	v_lshl_add_u64 v[156:157], v[156:157], 0, v[136:137]
	v_pk_mul_f32 v[166:167], v[72:73], v[166:167]
	v_pk_mul_f32 v[168:169], v[74:75], v[168:169]
	v_pk_mul_f32 v[166:167], v[96:97], v[166:167]
	v_pk_mul_f32 v[168:169], v[98:99], v[168:169]
	v_add_co_u32_e32 v156, vcc, s76, v156
	v_cvt_pk_bf16_f32 v166, v166, v167
	v_cvt_pk_bf16_f32 v167, v168, v169
	v_addc_co_u32_e32 v157, vcc, 0, v157, vcc
	v_mul_f32_e32 v153, 0xbfb8aa3b, v68
	global_store_dwordx4 v[156:157], v[164:167], off offset:3072 nt
	v_or_b32_e32 v156, 48, v152
	v_exp_f32_e32 v153, v153
	v_mul_f32_e32 v164, 0xbfb8aa3b, v69
	v_ashrrev_i32_e32 v157, 31, v156
	v_exp_f32_e32 v165, v164
	v_lshlrev_b64 v[156:157], 11, v[156:157]
	v_lshl_add_u64 v[156:157], s[52:53], 0, v[156:157]
	v_lshl_add_u64 v[156:157], v[156:157], 0, v[136:137]
	v_add_f32_e32 v136, 1.0, v153
	v_mul_f32_e32 v153, 0xbfb8aa3b, v70
	v_rcp_f32_e32 v164, v136
	v_add_f32_e32 v136, 1.0, v165
	v_exp_f32_e32 v153, v153
	v_mul_f32_e32 v165, 0xbfb8aa3b, v71
	v_exp_f32_e32 v167, v165
	v_rcp_f32_e32 v165, v136
	v_add_f32_e32 v136, 1.0, v153
	v_rcp_f32_e32 v166, v136
	v_add_f32_e32 v136, 1.0, v167
	v_rcp_f32_e32 v167, v136
	v_mul_f32_e32 v136, 0xbfb8aa3b, v64
	v_exp_f32_e32 v136, v136
	v_mul_f32_e32 v153, 0xbfb8aa3b, v65
	v_exp_f32_e32 v153, v153
	v_pk_mul_f32 v[164:165], v[68:69], v[164:165]
	v_pk_mul_f32 v[166:167], v[70:71], v[166:167]
	v_pk_mul_f32 v[164:165], v[84:85], v[164:165]
	v_pk_mul_f32 v[166:167], v[86:87], v[166:167]
	v_add_f32_e32 v136, 1.0, v136
	v_cvt_pk_bf16_f32 v164, v164, v165
	v_cvt_pk_bf16_f32 v165, v166, v167
	v_rcp_f32_e32 v166, v136
	v_add_f32_e32 v136, 1.0, v153
	v_mul_f32_e32 v153, 0xbfb8aa3b, v66
	v_exp_f32_e32 v153, v153
	v_mul_f32_e32 v167, 0xbfb8aa3b, v67
	v_exp_f32_e32 v169, v167
	v_rcp_f32_e32 v167, v136
	v_add_f32_e32 v136, 1.0, v153
	v_rcp_f32_e32 v168, v136
	v_add_f32_e32 v136, 1.0, v169
	v_rcp_f32_e32 v169, v136
	v_mul_f32_e32 v136, 0xbfb8aa3b, v44
	v_exp_f32_e32 v136, v136
	v_mul_f32_e32 v153, 0xbfb8aa3b, v45
	v_exp_f32_e32 v153, v153
	v_pk_mul_f32 v[166:167], v[64:65], v[166:167]
	v_pk_mul_f32 v[168:169], v[66:67], v[168:169]
	v_pk_mul_f32 v[166:167], v[80:81], v[166:167]
	v_pk_mul_f32 v[168:169], v[82:83], v[168:169]
	v_add_co_u32_e32 v156, vcc, s76, v156
	v_cvt_pk_bf16_f32 v166, v166, v167
	v_cvt_pk_bf16_f32 v167, v168, v169
	v_addc_co_u32_e32 v157, vcc, 0, v157, vcc
	v_add_f32_e32 v136, 1.0, v136
	global_store_dwordx4 v[156:157], v[164:167], off offset:3072 nt
	v_rcp_f32_e32 v156, v136
	v_add_f32_e32 v136, 1.0, v153
	v_mul_f32_e32 v153, 0xbfb8aa3b, v46
	v_exp_f32_e32 v153, v153
	v_mul_f32_e32 v157, 0xbfb8aa3b, v47
	v_exp_f32_e32 v164, v157
	v_rcp_f32_e32 v157, v136
	v_add_f32_e32 v136, 1.0, v153
	v_rcp_f32_e32 v166, v136
	v_add_f32_e32 v136, 1.0, v164
	v_rcp_f32_e32 v167, v136
	v_mul_f32_e32 v136, 0xbfb8aa3b, v40
	v_exp_f32_e32 v136, v136
	v_mul_f32_e32 v153, 0xbfb8aa3b, v41
	v_pk_mul_f32 v[156:157], v[44:45], v[156:157]
	v_exp_f32_e32 v153, v153
	v_pk_mul_f32 v[156:157], v[60:61], v[156:157]
	v_add_f32_e32 v136, 1.0, v136
	v_cvt_pk_bf16_f32 v164, v156, v157
	v_pk_mul_f32 v[156:157], v[46:47], v[166:167]
	s_nop 0
	v_pk_mul_f32 v[156:157], v[62:63], v[156:157]
	s_nop 0
	v_cvt_pk_bf16_f32 v165, v156, v157
	v_rcp_f32_e32 v156, v136
	v_add_f32_e32 v136, 1.0, v153
	v_mul_f32_e32 v153, 0xbfb8aa3b, v42
	v_exp_f32_e32 v153, v153
	v_mul_f32_e32 v157, 0xbfb8aa3b, v43
	v_exp_f32_e32 v166, v157
	v_rcp_f32_e32 v157, v136
	v_add_f32_e32 v136, 1.0, v153
	v_rcp_f32_e32 v168, v136
	v_add_f32_e32 v136, 1.0, v166
	v_rcp_f32_e32 v169, v136
	v_pk_mul_f32 v[156:157], v[40:41], v[156:157]
	v_mul_f32_e32 v136, 0xbfb8aa3b, v28
	v_pk_mul_f32 v[156:157], v[56:57], v[156:157]
	v_exp_f32_e32 v136, v136
	v_mul_f32_e32 v153, 0xbfb8aa3b, v29
	v_cvt_pk_bf16_f32 v166, v156, v157
	v_pk_mul_f32 v[156:157], v[42:43], v[168:169]
	v_exp_f32_e32 v153, v153
	v_pk_mul_f32 v[156:157], v[58:59], v[156:157]
	v_add_f32_e32 v136, 1.0, v136
	v_cvt_pk_bf16_f32 v167, v156, v157
	v_add_co_u32_e32 v156, vcc, s77, v154
	s_nop 1
	v_addc_co_u32_e32 v157, vcc, 0, v155, vcc
	global_store_dwordx4 v[156:157], v[164:167], off offset:3072 nt
	v_rcp_f32_e32 v156, v136
	v_add_f32_e32 v136, 1.0, v153
	v_mul_f32_e32 v153, 0xbfb8aa3b, v30
	v_exp_f32_e32 v153, v153
	v_mul_f32_e32 v157, 0xbfb8aa3b, v31
	v_exp_f32_e32 v164, v157
	v_rcp_f32_e32 v157, v136
	v_add_f32_e32 v136, 1.0, v153
	v_rcp_f32_e32 v166, v136
	v_add_f32_e32 v136, 1.0, v164
	v_rcp_f32_e32 v167, v136
	v_mul_f32_e32 v136, 0xbfb8aa3b, v24
	v_exp_f32_e32 v136, v136
	v_mul_f32_e32 v153, 0xbfb8aa3b, v25
	v_pk_mul_f32 v[156:157], v[28:29], v[156:157]
	v_exp_f32_e32 v153, v153
	v_pk_mul_f32 v[156:157], v[52:53], v[156:157]
	v_add_f32_e32 v136, 1.0, v136
	v_cvt_pk_bf16_f32 v164, v156, v157
	v_pk_mul_f32 v[156:157], v[30:31], v[166:167]
	s_nop 0
	v_pk_mul_f32 v[156:157], v[54:55], v[156:157]
	s_nop 0
	v_cvt_pk_bf16_f32 v165, v156, v157
	v_rcp_f32_e32 v156, v136
	v_add_f32_e32 v136, 1.0, v153
	v_mul_f32_e32 v153, 0xbfb8aa3b, v26
	v_exp_f32_e32 v153, v153
	v_mul_f32_e32 v157, 0xbfb8aa3b, v27
	v_exp_f32_e32 v166, v157
	v_rcp_f32_e32 v157, v136
	v_add_f32_e32 v136, 1.0, v153
	v_rcp_f32_e32 v168, v136
	v_add_f32_e32 v136, 1.0, v166
	v_rcp_f32_e32 v169, v136
	v_pk_mul_f32 v[156:157], v[24:25], v[156:157]
	v_mul_f32_e32 v136, 0xbfb8aa3b, v12
	v_pk_mul_f32 v[156:157], v[48:49], v[156:157]
	v_exp_f32_e32 v136, v136
	v_mul_f32_e32 v153, 0xbfb8aa3b, v13
	v_cvt_pk_bf16_f32 v166, v156, v157
	v_pk_mul_f32 v[156:157], v[26:27], v[168:169]
	v_exp_f32_e32 v153, v153
	v_pk_mul_f32 v[156:157], v[50:51], v[156:157]
	v_add_f32_e32 v136, 1.0, v136
	v_cvt_pk_bf16_f32 v167, v156, v157
	v_add_co_u32_e32 v156, vcc, s78, v154
	s_nop 1
	v_addc_co_u32_e32 v157, vcc, 0, v155, vcc
	global_store_dwordx4 v[156:157], v[164:167], off offset:3072 nt
	v_rcp_f32_e32 v156, v136
	v_add_f32_e32 v136, 1.0, v153
	v_mul_f32_e32 v153, 0xbfb8aa3b, v14
	v_exp_f32_e32 v153, v153
	v_mul_f32_e32 v157, 0xbfb8aa3b, v15
	v_exp_f32_e32 v164, v157
	v_rcp_f32_e32 v157, v136
	v_add_f32_e32 v136, 1.0, v153
	v_rcp_f32_e32 v166, v136
	v_add_f32_e32 v136, 1.0, v164
	v_rcp_f32_e32 v167, v136
	v_mul_f32_e32 v136, 0xbfb8aa3b, v8
	v_exp_f32_e32 v136, v136
	v_mul_f32_e32 v153, 0xbfb8aa3b, v9
	v_pk_mul_f32 v[156:157], v[12:13], v[156:157]
	v_exp_f32_e32 v153, v153
	v_pk_mul_f32 v[156:157], v[36:37], v[156:157]
	v_add_f32_e32 v136, 1.0, v136
	v_cvt_pk_bf16_f32 v164, v156, v157
	v_pk_mul_f32 v[156:157], v[14:15], v[166:167]
	s_nop 0
	v_pk_mul_f32 v[156:157], v[38:39], v[156:157]
	s_nop 0
	v_cvt_pk_bf16_f32 v165, v156, v157
	v_rcp_f32_e32 v156, v136
	v_add_f32_e32 v136, 1.0, v153
	v_mul_f32_e32 v153, 0xbfb8aa3b, v10
	v_exp_f32_e32 v153, v153
	v_mul_f32_e32 v157, 0xbfb8aa3b, v11
	v_exp_f32_e32 v166, v157
	v_rcp_f32_e32 v157, v136
	v_add_f32_e32 v136, 1.0, v153
	v_rcp_f32_e32 v168, v136
	v_add_f32_e32 v136, 1.0, v166
	v_rcp_f32_e32 v169, v136
	v_pk_mul_f32 v[156:157], v[8:9], v[156:157]
	v_mul_f32_e32 v136, 0xbfb8aa3b, v4
	v_pk_mul_f32 v[156:157], v[32:33], v[156:157]
	v_exp_f32_e32 v136, v136
	v_mul_f32_e32 v153, 0xbfb8aa3b, v5
	v_cvt_pk_bf16_f32 v166, v156, v157
	v_pk_mul_f32 v[156:157], v[10:11], v[168:169]
	v_exp_f32_e32 v153, v153
	v_pk_mul_f32 v[156:157], v[34:35], v[156:157]
	v_add_f32_e32 v136, 1.0, v136
	v_cvt_pk_bf16_f32 v167, v156, v157
	v_add_co_u32_e32 v156, vcc, s79, v154
	s_nop 1
	v_addc_co_u32_e32 v157, vcc, 0, v155, vcc
	global_store_dwordx4 v[156:157], v[164:167], off offset:3072 nt
	v_rcp_f32_e32 v156, v136
	v_add_f32_e32 v136, 1.0, v153
	v_mul_f32_e32 v153, 0xbfb8aa3b, v6
	v_exp_f32_e32 v153, v153
	v_mul_f32_e32 v157, 0xbfb8aa3b, v7
	v_exp_f32_e32 v164, v157
	v_rcp_f32_e32 v157, v136
	v_add_f32_e32 v136, 1.0, v153
	v_rcp_f32_e32 v166, v136
	v_add_f32_e32 v136, 1.0, v164
	v_rcp_f32_e32 v167, v136
	v_mul_f32_e32 v136, 0xbfb8aa3b, v0
	v_exp_f32_e32 v136, v136
	v_mul_f32_e32 v153, 0xbfb8aa3b, v1
	v_pk_mul_f32 v[156:157], v[4:5], v[156:157]
	v_exp_f32_e32 v153, v153
	v_pk_mul_f32 v[156:157], v[20:21], v[156:157]
	v_add_f32_e32 v136, 1.0, v136
	v_cvt_pk_bf16_f32 v164, v156, v157
	v_pk_mul_f32 v[156:157], v[6:7], v[166:167]
	v_add_co_u32_e32 v154, vcc, 0x1a056000, v154
	v_pk_mul_f32 v[156:157], v[22:23], v[156:157]
	s_nop 0
	v_addc_co_u32_e32 v155, vcc, 0, v155, vcc
	v_cvt_pk_bf16_f32 v165, v156, v157
	v_rcp_f32_e32 v156, v136
	v_add_f32_e32 v136, 1.0, v153
	v_mul_f32_e32 v153, 0xbfb8aa3b, v2
	v_exp_f32_e32 v153, v153
	v_mul_f32_e32 v157, 0xbfb8aa3b, v3
	v_exp_f32_e32 v166, v157
	v_rcp_f32_e32 v157, v136
	v_add_f32_e32 v136, 1.0, v153
	v_rcp_f32_e32 v168, v136
	v_add_f32_e32 v136, 1.0, v166
	v_rcp_f32_e32 v169, v136
	v_pk_mul_f32 v[156:157], v[0:1], v[156:157]
	s_nop 0
	v_pk_mul_f32 v[156:157], v[16:17], v[156:157]
	s_nop 0
	v_cvt_pk_bf16_f32 v166, v156, v157
	v_pk_mul_f32 v[156:157], v[2:3], v[168:169]
	s_nop 0
	v_pk_mul_f32 v[156:157], v[18:19], v[156:157]
	s_nop 0
	v_cvt_pk_bf16_f32 v167, v156, v157
	global_store_dwordx4 v[154:155], v[164:167], off offset:3072 nt

.LBB0_204:
	s_andn2_b64 vcc, exec, s[52:53]
	s_cbranch_vccnz .LBB0_206
	s_mov_b32 s32, 16
	s_lshl_b32 s47, s94, 8
	s_add_u32 s52, s10, s47
	v_ashrrev_i32_e32 v153, 31, v152
	s_addc_u32 s53, s11, 0
	v_lshlrev_b64 v[154:155], 11, v[152:153]
	v_lshl_add_u64 v[164:165], s[52:53], 0, v[154:155]
	v_lshlrev_b32_e32 v136, 1, v138
	v_pk_mul_f32 v[156:157], v[126:127], v[110:111]
	v_pk_mul_f32 v[154:155], v[124:125], v[108:109]
	v_pk_mul_f32 v[166:167], v[122:123], v[106:107]
	v_lshl_add_u64 v[164:165], v[164:165], 0, v[136:137]
	v_pk_mul_f32 v[168:169], v[120:121], v[104:105]
	v_cvt_pk_bf16_f32 v154, v154, v155
	v_cvt_pk_bf16_f32 v155, v156, v157
	v_cvt_pk_bf16_f32 v157, v166, v167
	v_add_co_u32_e32 v166, vcc, s80, v164
	v_cvt_pk_bf16_f32 v156, v168, v169
	s_nop 0
	v_addc_co_u32_e32 v167, vcc, 0, v165, vcc
	global_store_dwordx4 v[166:167], v[154:157], off offset:1024 nt
	v_pk_mul_f32 v[168:169], v[114:115], v[90:91]
	v_pk_mul_f32 v[170:171], v[112:113], v[88:89]
	v_or_b32_e32 v154, 16, v152
	v_ashrrev_i32_e32 v155, 31, v154
	v_lshlrev_b64 v[154:155], 11, v[154:155]
	v_lshl_add_u64 v[154:155], s[52:53], 0, v[154:155]
	v_lshl_add_u64 v[166:167], v[154:155], 0, v[136:137]
	v_pk_mul_f32 v[156:157], v[118:119], v[94:95]
	v_pk_mul_f32 v[154:155], v[116:117], v[92:93]
	v_add_co_u32_e32 v166, vcc, s80, v166
	v_cvt_pk_bf16_f32 v154, v154, v155
	v_cvt_pk_bf16_f32 v155, v156, v157
	v_cvt_pk_bf16_f32 v156, v170, v171
	v_cvt_pk_bf16_f32 v157, v168, v169
	v_addc_co_u32_e32 v167, vcc, 0, v167, vcc
	global_store_dwordx4 v[166:167], v[154:157], off offset:1024 nt
	v_pk_mul_f32 v[168:169], v[98:99], v[74:75]
	v_pk_mul_f32 v[170:171], v[96:97], v[72:73]
	v_or_b32_e32 v154, 32, v152
	v_ashrrev_i32_e32 v155, 31, v154
	v_lshlrev_b64 v[154:155], 11, v[154:155]
	v_lshl_add_u64 v[154:155], s[52:53], 0, v[154:155]
	v_lshl_add_u64 v[166:167], v[154:155], 0, v[136:137]
	v_pk_mul_f32 v[156:157], v[102:103], v[78:79]
	v_pk_mul_f32 v[154:155], v[100:101], v[76:77]
	v_add_co_u32_e32 v166, vcc, s80, v166
	v_cvt_pk_bf16_f32 v154, v154, v155
	v_cvt_pk_bf16_f32 v155, v156, v157
	v_cvt_pk_bf16_f32 v156, v170, v171
	v_cvt_pk_bf16_f32 v157, v168, v169
	v_addc_co_u32_e32 v167, vcc, 0, v167, vcc
	global_store_dwordx4 v[166:167], v[154:157], off offset:1024 nt
	v_pk_mul_f32 v[168:169], v[82:83], v[66:67]
	v_pk_mul_f32 v[170:171], v[80:81], v[64:65]
	v_or_b32_e32 v154, 48, v152
	v_ashrrev_i32_e32 v155, 31, v154
	v_lshlrev_b64 v[154:155], 11, v[154:155]
	v_lshl_add_u64 v[154:155], s[52:53], 0, v[154:155]
	v_lshl_add_u64 v[166:167], v[154:155], 0, v[136:137]
	v_pk_mul_f32 v[156:157], v[86:87], v[70:71]
	v_pk_mul_f32 v[154:155], v[84:85], v[68:69]
	v_add_co_u32_e32 v166, vcc, s80, v166
	v_cvt_pk_bf16_f32 v154, v154, v155
	v_cvt_pk_bf16_f32 v155, v156, v157
	v_cvt_pk_bf16_f32 v156, v170, v171
	v_cvt_pk_bf16_f32 v157, v168, v169
	v_addc_co_u32_e32 v167, vcc, 0, v167, vcc
	global_store_dwordx4 v[166:167], v[154:157], off offset:1024 nt
	v_pk_mul_f32 v[166:167], v[58:59], v[42:43]
	v_pk_mul_f32 v[168:169], v[56:57], v[40:41]
	v_pk_mul_f32 v[156:157], v[62:63], v[46:47]
	v_pk_mul_f32 v[154:155], v[60:61], v[44:45]
	s_nop 0
	v_cvt_pk_bf16_f32 v154, v154, v155
	v_cvt_pk_bf16_f32 v155, v156, v157
	v_cvt_pk_bf16_f32 v157, v166, v167
	v_add_co_u32_e32 v166, vcc, s81, v164
	v_cvt_pk_bf16_f32 v156, v168, v169
	s_nop 0
	v_addc_co_u32_e32 v167, vcc, 0, v165, vcc
	global_store_dwordx4 v[166:167], v[154:157], off offset:1024 nt
	v_pk_mul_f32 v[166:167], v[50:51], v[26:27]
	v_pk_mul_f32 v[168:169], v[48:49], v[24:25]
	v_pk_mul_f32 v[156:157], v[54:55], v[30:31]
	v_pk_mul_f32 v[154:155], v[52:53], v[28:29]
	s_nop 0
	v_cvt_pk_bf16_f32 v154, v154, v155
	v_cvt_pk_bf16_f32 v155, v156, v157
	v_cvt_pk_bf16_f32 v157, v166, v167
	v_add_co_u32_e32 v166, vcc, s82, v164
	v_cvt_pk_bf16_f32 v156, v168, v169
	s_nop 0
	v_addc_co_u32_e32 v167, vcc, 0, v165, vcc
	global_store_dwordx4 v[166:167], v[154:157], off offset:1024 nt
	v_pk_mul_f32 v[166:167], v[34:35], v[10:11]
	v_pk_mul_f32 v[168:169], v[32:33], v[8:9]
	v_pk_mul_f32 v[156:157], v[38:39], v[14:15]
	v_pk_mul_f32 v[154:155], v[36:37], v[12:13]
	s_nop 0
	v_cvt_pk_bf16_f32 v154, v154, v155
	v_cvt_pk_bf16_f32 v155, v156, v157
	v_cvt_pk_bf16_f32 v157, v166, v167
	v_add_co_u32_e32 v166, vcc, s83, v164
	v_cvt_pk_bf16_f32 v156, v168, v169
	s_nop 0
	v_addc_co_u32_e32 v167, vcc, 0, v165, vcc
	global_store_dwordx4 v[166:167], v[154:157], off offset:1024 nt
	v_pk_mul_f32 v[166:167], v[18:19], v[2:3]
	v_pk_mul_f32 v[168:169], v[16:17], v[0:1]
	v_pk_mul_f32 v[156:157], v[22:23], v[6:7]
	v_pk_mul_f32 v[154:155], v[20:21], v[4:5]
	v_add_co_u32_e32 v164, vcc, 0x16057000, v164
	v_cvt_pk_bf16_f32 v154, v154, v155
	v_cvt_pk_bf16_f32 v155, v156, v157
	v_cvt_pk_bf16_f32 v156, v168, v169
	v_cvt_pk_bf16_f32 v157, v166, v167
	v_addc_co_u32_e32 v165, vcc, 0, v165, vcc
	global_store_dwordx4 v[164:165], v[154:157], off offset:1024 nt

.LBB0_207:
	s_andn2_b64 vcc, exec, s[52:53]
	s_cbranch_vccnz .LBB0_209
	s_mov_b32 s32, 24
	s_lshl_b32 s47, s94, 9
	s_add_u32 s52, s10, s47
	v_ashrrev_i32_e32 v153, 31, v152
	s_addc_u32 s53, s11, 0
	v_lshlrev_b64 v[154:155], 11, v[152:153]
	v_lshl_add_u64 v[154:155], s[52:53], 0, v[154:155]
	v_lshlrev_b32_e32 v136, 1, v138
	v_lshl_add_u64 v[164:165], v[154:155], 0, v[136:137]
	v_add_co_u32_e32 v168, vcc, s84, v164
	v_cvt_pk_bf16_f32 v154, v124, v125
	v_cvt_pk_bf16_f32 v155, v126, v127
	v_cvt_pk_bf16_f32 v156, v120, v121
	v_cvt_pk_bf16_f32 v157, v122, v123
	v_addc_co_u32_e32 v169, vcc, 0, v165, vcc
	v_lshl_add_u64 v[166:167], v[164:165], 0, s[22:23]
	global_store_dwordx4 v[168:169], v[154:157], off nt
	s_nop 1
	v_cvt_pk_bf16_f32 v154, v108, v109
	v_cvt_pk_bf16_f32 v155, v110, v111
	v_cvt_pk_bf16_f32 v156, v104, v105
	v_cvt_pk_bf16_f32 v157, v106, v107
	global_store_dwordx4 v[166:167], v[154:157], off offset:256 nt
	s_nop 1
	v_or_b32_e32 v154, 16, v152
	v_ashrrev_i32_e32 v155, 31, v154
	v_lshlrev_b64 v[154:155], 11, v[154:155]
	v_lshl_add_u64 v[154:155], s[52:53], 0, v[154:155]
	v_lshl_add_u64 v[166:167], v[154:155], 0, v[136:137]
	v_lshl_add_u64 v[168:169], v[166:167], 0, s[22:23]
	v_add_co_u32_e32 v166, vcc, s84, v166
	v_cvt_pk_bf16_f32 v154, v116, v117
	v_cvt_pk_bf16_f32 v155, v118, v119
	v_cvt_pk_bf16_f32 v156, v112, v113
	v_cvt_pk_bf16_f32 v157, v114, v115
	v_addc_co_u32_e32 v167, vcc, 0, v167, vcc
	global_store_dwordx4 v[166:167], v[154:157], off nt
	s_nop 1
	v_cvt_pk_bf16_f32 v154, v92, v93
	v_cvt_pk_bf16_f32 v155, v94, v95
	v_cvt_pk_bf16_f32 v156, v88, v89
	v_cvt_pk_bf16_f32 v157, v90, v91
	global_store_dwordx4 v[168:169], v[154:157], off offset:256 nt
	s_nop 1
	v_or_b32_e32 v154, 32, v152
	v_ashrrev_i32_e32 v155, 31, v154
	v_lshlrev_b64 v[154:155], 11, v[154:155]
	v_lshl_add_u64 v[154:155], s[52:53], 0, v[154:155]
	v_lshl_add_u64 v[166:167], v[154:155], 0, v[136:137]
	v_lshl_add_u64 v[168:169], v[166:167], 0, s[22:23]
	v_add_co_u32_e32 v166, vcc, s84, v166
	v_cvt_pk_bf16_f32 v154, v100, v101
	v_cvt_pk_bf16_f32 v155, v102, v103
	v_cvt_pk_bf16_f32 v156, v96, v97
	v_cvt_pk_bf16_f32 v157, v98, v99
	v_addc_co_u32_e32 v167, vcc, 0, v167, vcc
	global_store_dwordx4 v[166:167], v[154:157], off nt
	s_nop 1
	v_cvt_pk_bf16_f32 v154, v76, v77
	v_cvt_pk_bf16_f32 v155, v78, v79
	v_cvt_pk_bf16_f32 v156, v72, v73
	v_cvt_pk_bf16_f32 v157, v74, v75
	global_store_dwordx4 v[168:169], v[154:157], off offset:256 nt
	s_nop 1
	v_or_b32_e32 v154, 48, v152
	v_ashrrev_i32_e32 v155, 31, v154
	v_lshlrev_b64 v[154:155], 11, v[154:155]
	v_lshl_add_u64 v[154:155], s[52:53], 0, v[154:155]
	v_lshl_add_u64 v[166:167], v[154:155], 0, v[136:137]
	v_lshl_add_u64 v[168:169], v[166:167], 0, s[22:23]
	v_add_co_u32_e32 v166, vcc, s84, v166
	v_cvt_pk_bf16_f32 v154, v84, v85
	v_cvt_pk_bf16_f32 v155, v86, v87
	v_cvt_pk_bf16_f32 v156, v80, v81
	v_cvt_pk_bf16_f32 v157, v82, v83
	v_addc_co_u32_e32 v167, vcc, 0, v167, vcc
	global_store_dwordx4 v[166:167], v[154:157], off nt
	v_lshl_add_u64 v[166:167], v[164:165], 0, s[24:25]
	s_nop 0
	v_cvt_pk_bf16_f32 v154, v68, v69
	v_cvt_pk_bf16_f32 v155, v70, v71
	v_cvt_pk_bf16_f32 v156, v64, v65
	v_cvt_pk_bf16_f32 v157, v66, v67
	global_store_dwordx4 v[168:169], v[154:157], off offset:256 nt
	v_add_co_u32_e32 v168, vcc, s85, v164
	s_nop 0
	v_cvt_pk_bf16_f32 v154, v60, v61
	v_cvt_pk_bf16_f32 v155, v62, v63
	v_cvt_pk_bf16_f32 v156, v56, v57
	v_cvt_pk_bf16_f32 v157, v58, v59
	v_addc_co_u32_e32 v169, vcc, 0, v165, vcc
	global_store_dwordx4 v[168:169], v[154:157], off nt
	v_add_co_u32_e32 v168, vcc, s86, v164
	s_nop 0
	v_cvt_pk_bf16_f32 v154, v44, v45
	v_cvt_pk_bf16_f32 v155, v46, v47
	v_cvt_pk_bf16_f32 v156, v40, v41
	v_cvt_pk_bf16_f32 v157, v42, v43
	global_store_dwordx4 v[166:167], v[154:157], off offset:256 nt
	v_addc_co_u32_e32 v169, vcc, 0, v165, vcc
	s_nop 0
	v_cvt_pk_bf16_f32 v154, v52, v53
	v_cvt_pk_bf16_f32 v155, v54, v55
	v_cvt_pk_bf16_f32 v156, v48, v49
	v_cvt_pk_bf16_f32 v157, v50, v51
	v_lshl_add_u64 v[166:167], v[164:165], 0, s[26:27]
	global_store_dwordx4 v[168:169], v[154:157], off nt
	v_add_co_u32_e32 v168, vcc, s87, v164
	s_nop 0
	v_cvt_pk_bf16_f32 v154, v28, v29
	v_cvt_pk_bf16_f32 v155, v30, v31
	v_cvt_pk_bf16_f32 v156, v24, v25
	v_cvt_pk_bf16_f32 v157, v26, v27
	global_store_dwordx4 v[166:167], v[154:157], off offset:256 nt
	v_addc_co_u32_e32 v169, vcc, 0, v165, vcc
	s_nop 0
	v_cvt_pk_bf16_f32 v154, v36, v37
	v_cvt_pk_bf16_f32 v155, v38, v39
	v_cvt_pk_bf16_f32 v156, v32, v33
	v_cvt_pk_bf16_f32 v157, v34, v35
	v_lshl_add_u64 v[166:167], v[164:165], 0, s[28:29]
	global_store_dwordx4 v[168:169], v[154:157], off nt
	s_nop 1
	v_cvt_pk_bf16_f32 v154, v12, v13
	v_cvt_pk_bf16_f32 v155, v14, v15
	v_cvt_pk_bf16_f32 v156, v8, v9
	v_cvt_pk_bf16_f32 v157, v10, v11
	global_store_dwordx4 v[166:167], v[154:157], off offset:256 nt
	v_lshl_add_u64 v[166:167], v[164:165], 0, s[30:31]
	v_add_co_u32_e32 v164, vcc, s88, v164
	v_cvt_pk_bf16_f32 v154, v20, v21
	v_cvt_pk_bf16_f32 v155, v22, v23
	v_cvt_pk_bf16_f32 v156, v16, v17
	v_cvt_pk_bf16_f32 v157, v18, v19
	v_addc_co_u32_e32 v165, vcc, 0, v165, vcc
	global_store_dwordx4 v[164:165], v[154:157], off nt
	s_nop 1
	v_cvt_pk_bf16_f32 v154, v4, v5
	v_cvt_pk_bf16_f32 v155, v6, v7
	v_cvt_pk_bf16_f32 v156, v0, v1
	v_cvt_pk_bf16_f32 v157, v2, v3
	global_store_dwordx4 v[166:167], v[154:157], off offset:256 nt

.LBB0_210:
	s_andn2_b64 vcc, exec, s[52:53]
	s_cbranch_vccnz .LBB0_212
	s_mov_b32 s32, 24
	s_lshl_b32 s47, s94, 8
	s_add_i32 s54, s47, 0xfffffe00
	s_cmp_lt_i32 s94, 2
	s_cselect_b64 vcc, -1, 0
	s_and_b64 s[52:53], vcc, exec
	s_cselect_b32 s52, s47, s54
	s_cselect_b32 s47, s89, 0x14000000
	s_add_u32 s47, s10, s47
	s_addc_u32 s54, s11, 0
	s_ashr_i32 s53, s52, 31
	s_lshl_b64 s[52:53], s[52:53], 1
	s_add_u32 s52, s47, s52
	v_cndmask_b32_e32 v154, 1.0, v163, vcc
	s_addc_u32 s53, s54, s53
	v_lshlrev_b32_e32 v136, 1, v138
	v_ashrrev_i32_e32 v153, 31, v152
	v_lshl_add_u64 v[168:169], s[52:53], 0, v[136:137]
	v_lshlrev_b64 v[156:157], 10, v[152:153]
	v_pk_mul_f32 v[166:167], v[154:155], v[126:127] op_sel_hi:[0,1]
	v_pk_mul_f32 v[164:165], v[154:155], v[124:125] op_sel_hi:[0,1]
	v_pk_mul_f32 v[170:171], v[154:155], v[122:123] op_sel_hi:[0,1]
	v_pk_mul_f32 v[172:173], v[154:155], v[120:121] op_sel_hi:[0,1]
	v_lshl_add_u64 v[156:157], v[168:169], 0, v[156:157]
	v_cvt_pk_bf16_f32 v164, v164, v165
	v_cvt_pk_bf16_f32 v165, v166, v167
	v_cvt_pk_bf16_f32 v166, v172, v173
	v_cvt_pk_bf16_f32 v167, v170, v171
	global_store_dwordx4 v[156:157], v[164:167], off nt
	v_pk_mul_f32 v[170:171], v[154:155], v[106:107] op_sel_hi:[0,1]
	v_pk_mul_f32 v[172:173], v[154:155], v[104:105] op_sel_hi:[0,1]
	v_pk_mul_f32 v[166:167], v[154:155], v[110:111] op_sel_hi:[0,1]
	v_pk_mul_f32 v[164:165], v[154:155], v[108:109] op_sel_hi:[0,1]
	v_cvt_pk_bf16_f32 v164, v164, v165
	v_cvt_pk_bf16_f32 v165, v166, v167
	v_cvt_pk_bf16_f32 v166, v172, v173
	v_cvt_pk_bf16_f32 v167, v170, v171
	global_store_dwordx4 v[156:157], v[164:167], off offset:256 nt
	v_pk_mul_f32 v[172:173], v[154:155], v[114:115] op_sel_hi:[0,1]
	v_pk_mul_f32 v[174:175], v[154:155], v[112:113] op_sel_hi:[0,1]
	v_or_b32_e32 v164, 16, v152
	v_ashrrev_i32_e32 v165, 31, v164
	v_lshlrev_b64 v[164:165], 10, v[164:165]
	v_lshl_add_u64 v[170:171], v[168:169], 0, v[164:165]
	v_pk_mul_f32 v[166:167], v[154:155], v[118:119] op_sel_hi:[0,1]
	v_pk_mul_f32 v[164:165], v[154:155], v[116:117] op_sel_hi:[0,1]
	v_cvt_pk_bf16_f32 v164, v164, v165
	v_cvt_pk_bf16_f32 v165, v166, v167
	v_cvt_pk_bf16_f32 v166, v174, v175
	v_cvt_pk_bf16_f32 v167, v172, v173
	global_store_dwordx4 v[170:171], v[164:167], off nt
	v_pk_mul_f32 v[172:173], v[154:155], v[90:91] op_sel_hi:[0,1]
	v_pk_mul_f32 v[174:175], v[154:155], v[88:89] op_sel_hi:[0,1]
	v_pk_mul_f32 v[166:167], v[154:155], v[94:95] op_sel_hi:[0,1]
	v_pk_mul_f32 v[164:165], v[154:155], v[92:93] op_sel_hi:[0,1]
	v_cvt_pk_bf16_f32 v164, v164, v165
	v_cvt_pk_bf16_f32 v165, v166, v167
	v_cvt_pk_bf16_f32 v166, v174, v175
	v_cvt_pk_bf16_f32 v167, v172, v173
	global_store_dwordx4 v[170:171], v[164:167], off offset:256 nt
	v_pk_mul_f32 v[172:173], v[154:155], v[98:99] op_sel_hi:[0,1]
	v_pk_mul_f32 v[174:175], v[154:155], v[96:97] op_sel_hi:[0,1]
	v_or_b32_e32 v164, 32, v152
	v_ashrrev_i32_e32 v165, 31, v164
	v_lshlrev_b64 v[164:165], 10, v[164:165]
	v_lshl_add_u64 v[170:171], v[168:169], 0, v[164:165]
	v_pk_mul_f32 v[166:167], v[154:155], v[102:103] op_sel_hi:[0,1]
	v_pk_mul_f32 v[164:165], v[154:155], v[100:101] op_sel_hi:[0,1]
	v_cvt_pk_bf16_f32 v164, v164, v165
	v_cvt_pk_bf16_f32 v165, v166, v167
	v_cvt_pk_bf16_f32 v166, v174, v175
	v_cvt_pk_bf16_f32 v167, v172, v173
	global_store_dwordx4 v[170:171], v[164:167], off nt
	v_pk_mul_f32 v[172:173], v[154:155], v[74:75] op_sel_hi:[0,1]
	v_pk_mul_f32 v[174:175], v[154:155], v[72:73] op_sel_hi:[0,1]
	v_pk_mul_f32 v[166:167], v[154:155], v[78:79] op_sel_hi:[0,1]
	v_pk_mul_f32 v[164:165], v[154:155], v[76:77] op_sel_hi:[0,1]
	v_cvt_pk_bf16_f32 v164, v164, v165
	v_cvt_pk_bf16_f32 v165, v166, v167
	v_cvt_pk_bf16_f32 v166, v174, v175
	v_cvt_pk_bf16_f32 v167, v172, v173
	global_store_dwordx4 v[170:171], v[164:167], off offset:256 nt
	v_pk_mul_f32 v[170:171], v[154:155], v[82:83] op_sel_hi:[0,1]
	v_pk_mul_f32 v[172:173], v[154:155], v[80:81] op_sel_hi:[0,1]
	v_or_b32_e32 v164, 48, v152
	v_ashrrev_i32_e32 v165, 31, v164
	v_lshlrev_b64 v[164:165], 10, v[164:165]
	v_lshl_add_u64 v[168:169], v[168:169], 0, v[164:165]
	v_pk_mul_f32 v[166:167], v[154:155], v[86:87] op_sel_hi:[0,1]
	v_pk_mul_f32 v[164:165], v[154:155], v[84:85] op_sel_hi:[0,1]
	v_cvt_pk_bf16_f32 v164, v164, v165
	v_cvt_pk_bf16_f32 v165, v166, v167
	v_cvt_pk_bf16_f32 v166, v172, v173
	v_cvt_pk_bf16_f32 v167, v170, v171
	global_store_dwordx4 v[168:169], v[164:167], off nt
	v_pk_mul_f32 v[170:171], v[154:155], v[66:67] op_sel_hi:[0,1]
	v_pk_mul_f32 v[172:173], v[154:155], v[64:65] op_sel_hi:[0,1]
	v_pk_mul_f32 v[166:167], v[154:155], v[70:71] op_sel_hi:[0,1]
	v_pk_mul_f32 v[164:165], v[154:155], v[68:69] op_sel_hi:[0,1]
	v_cvt_pk_bf16_f32 v164, v164, v165
	v_cvt_pk_bf16_f32 v165, v166, v167
	v_cvt_pk_bf16_f32 v166, v172, v173
	v_cvt_pk_bf16_f32 v167, v170, v171
	global_store_dwordx4 v[168:169], v[164:167], off offset:256 nt
	v_pk_mul_f32 v[170:171], v[154:155], v[58:59] op_sel_hi:[0,1]
	v_pk_mul_f32 v[172:173], v[154:155], v[56:57] op_sel_hi:[0,1]
	v_pk_mul_f32 v[166:167], v[154:155], v[62:63] op_sel_hi:[0,1]
	v_pk_mul_f32 v[164:165], v[154:155], v[60:61] op_sel_hi:[0,1]
	v_cvt_pk_bf16_f32 v164, v164, v165
	v_cvt_pk_bf16_f32 v165, v166, v167
	v_cvt_pk_bf16_f32 v167, v170, v171
	v_add_co_u32_e32 v170, vcc, s90, v156
	v_cvt_pk_bf16_f32 v166, v172, v173
	s_nop 0
	v_addc_co_u32_e32 v171, vcc, 0, v157, vcc
	global_store_dwordx4 v[170:171], v[164:167], off nt
	v_pk_mul_f32 v[170:171], v[154:155], v[42:43] op_sel_hi:[0,1]
	v_pk_mul_f32 v[172:173], v[154:155], v[40:41] op_sel_hi:[0,1]
	v_pk_mul_f32 v[166:167], v[154:155], v[46:47] op_sel_hi:[0,1]
	v_pk_mul_f32 v[164:165], v[154:155], v[44:45] op_sel_hi:[0,1]
	v_lshl_add_u64 v[168:169], v[156:157], 0, s[34:35]
	v_cvt_pk_bf16_f32 v164, v164, v165
	v_cvt_pk_bf16_f32 v165, v166, v167
	v_cvt_pk_bf16_f32 v166, v172, v173
	v_cvt_pk_bf16_f32 v167, v170, v171
	global_store_dwordx4 v[168:169], v[164:167], off offset:256 nt
	v_pk_mul_f32 v[170:171], v[154:155], v[50:51] op_sel_hi:[0,1]
	v_pk_mul_f32 v[172:173], v[154:155], v[48:49] op_sel_hi:[0,1]
	v_pk_mul_f32 v[166:167], v[154:155], v[54:55] op_sel_hi:[0,1]
	v_pk_mul_f32 v[164:165], v[154:155], v[52:53] op_sel_hi:[0,1]
	v_cvt_pk_bf16_f32 v164, v164, v165
	v_cvt_pk_bf16_f32 v165, v166, v167
	v_cvt_pk_bf16_f32 v167, v170, v171
	v_add_co_u32_e32 v170, vcc, s91, v156
	v_cvt_pk_bf16_f32 v166, v172, v173
	s_nop 0
	v_addc_co_u32_e32 v171, vcc, 0, v157, vcc
	global_store_dwordx4 v[170:171], v[164:167], off nt
	v_pk_mul_f32 v[170:171], v[154:155], v[26:27] op_sel_hi:[0,1]
	v_pk_mul_f32 v[172:173], v[154:155], v[24:25] op_sel_hi:[0,1]
	v_pk_mul_f32 v[166:167], v[154:155], v[30:31] op_sel_hi:[0,1]
	v_pk_mul_f32 v[164:165], v[154:155], v[28:29] op_sel_hi:[0,1]
	v_lshl_add_u64 v[168:169], v[156:157], 0, s[36:37]
	v_cvt_pk_bf16_f32 v164, v164, v165
	v_cvt_pk_bf16_f32 v165, v166, v167
	v_cvt_pk_bf16_f32 v166, v172, v173
	v_cvt_pk_bf16_f32 v167, v170, v171
	global_store_dwordx4 v[168:169], v[164:167], off offset:256 nt
	v_pk_mul_f32 v[170:171], v[154:155], v[34:35] op_sel_hi:[0,1]
	v_pk_mul_f32 v[172:173], v[154:155], v[32:33] op_sel_hi:[0,1]
	v_pk_mul_f32 v[166:167], v[154:155], v[38:39] op_sel_hi:[0,1]
	v_pk_mul_f32 v[164:165], v[154:155], v[36:37] op_sel_hi:[0,1]
	v_cvt_pk_bf16_f32 v164, v164, v165
	v_cvt_pk_bf16_f32 v165, v166, v167
	v_cvt_pk_bf16_f32 v167, v170, v171
	v_add_co_u32_e32 v170, vcc, s92, v156
	v_cvt_pk_bf16_f32 v166, v172, v173
	s_nop 0
	v_addc_co_u32_e32 v171, vcc, 0, v157, vcc
	global_store_dwordx4 v[170:171], v[164:167], off nt
	v_pk_mul_f32 v[170:171], v[154:155], v[10:11] op_sel_hi:[0,1]
	v_pk_mul_f32 v[172:173], v[154:155], v[8:9] op_sel_hi:[0,1]
	v_pk_mul_f32 v[166:167], v[154:155], v[14:15] op_sel_hi:[0,1]
	v_pk_mul_f32 v[164:165], v[154:155], v[12:13] op_sel_hi:[0,1]
	v_lshl_add_u64 v[168:169], v[156:157], 0, s[38:39]
	v_cvt_pk_bf16_f32 v164, v164, v165
	v_cvt_pk_bf16_f32 v165, v166, v167
	v_cvt_pk_bf16_f32 v166, v172, v173
	v_cvt_pk_bf16_f32 v167, v170, v171
	global_store_dwordx4 v[168:169], v[164:167], off offset:256 nt
	v_lshl_add_u64 v[168:169], v[156:157], 0, s[42:43]
	v_pk_mul_f32 v[170:171], v[154:155], v[18:19] op_sel_hi:[0,1]
	v_pk_mul_f32 v[166:167], v[154:155], v[22:23] op_sel_hi:[0,1]
	v_pk_mul_f32 v[164:165], v[154:155], v[20:21] op_sel_hi:[0,1]
	v_pk_mul_f32 v[172:173], v[154:155], v[16:17] op_sel_hi:[0,1]
	v_add_co_u32_e32 v156, vcc, s93, v156
	v_cvt_pk_bf16_f32 v164, v164, v165
	v_cvt_pk_bf16_f32 v165, v166, v167
	v_cvt_pk_bf16_f32 v166, v172, v173
	v_cvt_pk_bf16_f32 v167, v170, v171
	v_addc_co_u32_e32 v157, vcc, 0, v157, vcc
	global_store_dwordx4 v[156:157], v[164:167], off nt
	v_pk_mul_f32 v[156:157], v[154:155], v[6:7] op_sel_hi:[0,1]
	v_pk_mul_f32 v[170:171], v[154:155], v[0:1] op_sel_hi:[0,1]
	v_pk_mul_f32 v[164:165], v[154:155], v[4:5] op_sel_hi:[0,1]
	v_pk_mul_f32 v[166:167], v[154:155], v[2:3] op_sel_hi:[0,1]
	v_cvt_pk_bf16_f32 v154, v164, v165
	v_cvt_pk_bf16_f32 v155, v156, v157
	v_cvt_pk_bf16_f32 v156, v170, v171
	v_cvt_pk_bf16_f32 v157, v166, v167
	global_store_dwordx4 v[168:169], v[154:157], off offset:256 nt

.LBB0_213:
	s_mov_b32 s32, 24
	s_lshr_b32 s45, s45, 10
	s_add_i32 s47, s94, 0x3fffc
	s_and_b32 s45, s45, 0x3fffc
	v_and_b32_e32 v136, 0xfcf, v152
	s_or_b32 s45, s45, s47
	v_lshl_or_b32 v136, s45, 14, v136
	v_or_b32_e32 v154, s72, v136
	v_cvt_pk_bf16_f32 v68, v68, v69
	v_cvt_pk_bf16_f32 v69, v70, v71
	v_cvt_pk_bf16_f32 v70, v64, v65
	v_or_b32_e32 v64, 0x2030, v154
	v_ashrrev_i32_e32 v65, 31, v64
	v_lshlrev_b64 v[64:65], 7, v[64:65]
	v_cvt_pk_bf16_f32 v71, v66, v67
	v_lshl_add_u64 v[64:65], v[142:143], 0, v[64:65]
	global_store_dwordx4 v[64:65], v[68:71], off nt
	v_add_u32_e32 v64, 0x80, v152
	v_and_b32_e32 v65, 0xfcf, v64
	v_lshrrev_b32_e32 v64, 10, v64
	v_cvt_pk_bf16_f32 v108, v108, v109
	v_cvt_pk_bf16_f32 v109, v110, v111
	v_cvt_pk_bf16_f32 v110, v104, v105
	v_or_b32_e32 v104, 0x2000, v154
	v_cvt_pk_bf16_f32 v92, v92, v93
	v_cvt_pk_bf16_f32 v93, v94, v95
	v_cvt_pk_bf16_f32 v94, v88, v89
	v_or_b32_e32 v88, 0x2010, v154
	v_cvt_pk_bf16_f32 v76, v76, v77
	v_cvt_pk_bf16_f32 v77, v78, v79
	v_cvt_pk_bf16_f32 v78, v72, v73
	v_or_b32_e32 v72, 0x2020, v154
	v_and_b32_e32 v64, 0x3fffc, v64
	v_ashrrev_i32_e32 v105, 31, v104
	v_ashrrev_i32_e32 v89, 31, v88
	v_ashrrev_i32_e32 v73, 31, v72
	v_or_b32_e32 v64, s47, v64
	v_lshlrev_b64 v[104:105], 7, v[104:105]
	v_lshlrev_b64 v[88:89], 7, v[88:89]
	v_lshlrev_b64 v[72:73], 7, v[72:73]
	v_lshlrev_b32_e32 v64, 14, v64
	v_cvt_pk_bf16_f32 v111, v106, v107
	v_lshl_add_u64 v[104:105], v[142:143], 0, v[104:105]
	v_cvt_pk_bf16_f32 v95, v90, v91
	v_lshl_add_u64 v[88:89], v[142:143], 0, v[88:89]
	v_cvt_pk_bf16_f32 v79, v74, v75
	v_lshl_add_u64 v[72:73], v[142:143], 0, v[72:73]
	v_or3_b32 v64, v64, v65, s72
	global_store_dwordx4 v[104:105], v[108:111], off nt
	global_store_dwordx4 v[88:89], v[92:95], off nt
	global_store_dwordx4 v[72:73], v[76:79], off nt
	v_or_b32_e32 v108, 16, v154
	v_or_b32_e32 v92, 32, v154
	v_or_b32_e32 v76, 48, v154
	v_cvt_pk_bf16_f32 v44, v44, v45
	v_cvt_pk_bf16_f32 v45, v46, v47
	v_cvt_pk_bf16_f32 v46, v40, v41
	v_or_b32_e32 v40, 0x2000, v64
	v_cvt_pk_bf16_f32 v28, v28, v29
	v_cvt_pk_bf16_f32 v29, v30, v31
	v_cvt_pk_bf16_f32 v30, v24, v25
	v_or_b32_e32 v24, 0x2010, v64
	v_cvt_pk_bf16_f32 v12, v12, v13
	v_cvt_pk_bf16_f32 v13, v14, v15
	v_cvt_pk_bf16_f32 v14, v8, v9
	v_or_b32_e32 v8, 0x2020, v64
	v_ashrrev_i32_e32 v155, 31, v154
	v_ashrrev_i32_e32 v109, 31, v108
	v_ashrrev_i32_e32 v93, 31, v92
	v_ashrrev_i32_e32 v77, 31, v76
	v_ashrrev_i32_e32 v41, 31, v40
	v_ashrrev_i32_e32 v25, 31, v24
	v_ashrrev_i32_e32 v9, 31, v8
	v_cvt_pk_bf16_f32 v124, v124, v125
	v_cvt_pk_bf16_f32 v125, v126, v127
	v_cvt_pk_bf16_f32 v126, v120, v121
	v_lshlrev_b64 v[120:121], 7, v[154:155]
	v_lshlrev_b64 v[108:109], 7, v[108:109]
	v_lshlrev_b64 v[92:93], 7, v[92:93]
	v_lshlrev_b64 v[76:77], 7, v[76:77]
	v_lshlrev_b64 v[40:41], 7, v[40:41]
	v_lshlrev_b64 v[24:25], 7, v[24:25]
	v_lshlrev_b64 v[8:9], 7, v[8:9]
	v_cvt_pk_bf16_f32 v127, v122, v123
	v_lshl_add_u64 v[120:121], v[142:143], 0, v[120:121]
	v_cvt_pk_bf16_f32 v104, v116, v117
	v_cvt_pk_bf16_f32 v105, v118, v119
	v_cvt_pk_bf16_f32 v106, v112, v113
	v_cvt_pk_bf16_f32 v107, v114, v115
	v_lshl_add_u64 v[108:109], v[142:143], 0, v[108:109]
	v_cvt_pk_bf16_f32 v88, v100, v101
	v_cvt_pk_bf16_f32 v89, v102, v103
	v_cvt_pk_bf16_f32 v90, v96, v97
	v_cvt_pk_bf16_f32 v91, v98, v99
	v_lshl_add_u64 v[92:93], v[142:143], 0, v[92:93]
	v_cvt_pk_bf16_f32 v72, v84, v85
	v_cvt_pk_bf16_f32 v73, v86, v87
	v_cvt_pk_bf16_f32 v74, v80, v81
	v_cvt_pk_bf16_f32 v75, v82, v83
	v_lshl_add_u64 v[76:77], v[142:143], 0, v[76:77]
	v_cvt_pk_bf16_f32 v47, v42, v43
	v_lshl_add_u64 v[40:41], v[142:143], 0, v[40:41]
	v_cvt_pk_bf16_f32 v31, v26, v27
	v_lshl_add_u64 v[24:25], v[142:143], 0, v[24:25]
	v_cvt_pk_bf16_f32 v15, v10, v11
	v_lshl_add_u64 v[8:9], v[142:143], 0, v[8:9]
	global_store_dwordx4 v[120:121], v[124:127], off nt
	global_store_dwordx4 v[108:109], v[104:107], off nt
	global_store_dwordx4 v[92:93], v[88:91], off nt
	global_store_dwordx4 v[76:77], v[72:75], off nt
	global_store_dwordx4 v[40:41], v[44:47], off nt
	global_store_dwordx4 v[24:25], v[28:31], off nt
	global_store_dwordx4 v[8:9], v[12:15], off nt
	v_or_b32_e32 v44, 16, v64
	v_or_b32_e32 v28, 32, v64
	v_or_b32_e32 v12, 48, v64
	v_cvt_pk_bf16_f32 v4, v4, v5
	v_cvt_pk_bf16_f32 v5, v6, v7
	v_cvt_pk_bf16_f32 v6, v0, v1
	v_or_b32_e32 v0, 0x2030, v64
	v_ashrrev_i32_e32 v65, 31, v64
	v_ashrrev_i32_e32 v45, 31, v44
	v_ashrrev_i32_e32 v29, 31, v28
	v_ashrrev_i32_e32 v13, 31, v12
	v_ashrrev_i32_e32 v1, 31, v0
	v_cvt_pk_bf16_f32 v60, v60, v61
	v_cvt_pk_bf16_f32 v61, v62, v63
	v_cvt_pk_bf16_f32 v62, v56, v57
	v_lshlrev_b64 v[56:57], 7, v[64:65]
	v_lshlrev_b64 v[44:45], 7, v[44:45]
	v_lshlrev_b64 v[28:29], 7, v[28:29]
	v_lshlrev_b64 v[12:13], 7, v[12:13]
	v_lshlrev_b64 v[0:1], 7, v[0:1]
	v_cvt_pk_bf16_f32 v63, v58, v59
	v_lshl_add_u64 v[56:57], v[142:143], 0, v[56:57]
	v_cvt_pk_bf16_f32 v40, v52, v53
	v_cvt_pk_bf16_f32 v41, v54, v55
	v_cvt_pk_bf16_f32 v42, v48, v49
	v_cvt_pk_bf16_f32 v43, v50, v51
	v_lshl_add_u64 v[44:45], v[142:143], 0, v[44:45]
	v_cvt_pk_bf16_f32 v24, v36, v37
	v_cvt_pk_bf16_f32 v25, v38, v39
	v_cvt_pk_bf16_f32 v26, v32, v33
	v_cvt_pk_bf16_f32 v27, v34, v35
	v_lshl_add_u64 v[28:29], v[142:143], 0, v[28:29]
	v_cvt_pk_bf16_f32 v8, v20, v21
	v_cvt_pk_bf16_f32 v9, v22, v23
	v_cvt_pk_bf16_f32 v10, v16, v17
	v_cvt_pk_bf16_f32 v11, v18, v19
	v_lshl_add_u64 v[12:13], v[142:143], 0, v[12:13]
	v_cvt_pk_bf16_f32 v7, v2, v3
	v_lshl_add_u64 v[0:1], v[142:143], 0, v[0:1]
	global_store_dwordx4 v[56:57], v[60:63], off nt
	global_store_dwordx4 v[44:45], v[40:43], off nt
	global_store_dwordx4 v[28:29], v[24:27], off nt
	global_store_dwordx4 v[12:13], v[8:11], off nt
	global_store_dwordx4 v[0:1], v[4:7], off nt
	s_andn2_b64 vcc, exec, s[6:7]
	s_mov_b64 s[6:7], -1
	s_cbranch_vccnz .LBB0_184

.LBB0_465:
	s_cmp_lt_i32 s40, 6
	s_cselect_b64 s[4:5], -1, 0
	s_and_b64 s[4:5], s[4:5], s[6:7]
	s_andn2_b64 vcc, exec, s[4:5]
	s_cbranch_vccnz .LBB0_519
	s_mov_b32 s32, 8
	s_mov_b64 s[4:5], s[0:1]
	s_load_dwordx2 s[10:11], s[4:5], 0x68
	s_load_dwordx4 s[12:15], s[4:5], 0x58
	s_cmpk_lt_i32 s2, 0x200
	s_cselect_b64 s[6:7], -1, 0
	s_cmpk_gt_i32 s2, 0x1ff
	v_readfirstlane_b32 s24, v158
	s_cbranch_scc1 .LBB0_472
	s_ashr_i32 s3, s2, 31
	s_lshr_b32 s3, s3, 29
	s_add_i32 s17, s2, s3
	s_and_b32 s3, s17, -8
	s_sub_i32 s3, s2, s3
	s_cmp_gt_i32 s3, -1
	s_cbranch_scc0 .LBB0_469
	s_lshl_b32 s16, s3, 6
	s_ashr_i32 s8, s17, 3
	s_cbranch_execz .LBB0_470
	s_branch .LBB0_471

.LBB0_485:
	ds_read_b128 v[140:143], v165
	ds_read_b128 v[144:147], v165 offset:1024
	ds_read_b128 v[148:151], v165 offset:2048
	ds_read_b128 v[152:155], v165 offset:3072
	ds_read_b128 v[156:159], v166
	ds_read_b128 v[172:175], v166 offset:1024
	ds_read_b128 v[176:179], v166 offset:2048
	ds_read_b128 v[180:183], v166 offset:3072
	s_add_u32 s46, s44, 0xfff80080
	s_addc_u32 s47, s45, -1
	s_cmp_eq_u32 s71, 28
	s_cselect_b32 s49, s9, s47
	s_cselect_b32 s48, s37, s46
	s_cselect_b32 s47, s35, s70
	s_cselect_b32 s46, s43, s69
	v_lshl_add_u64 v[160:161], s[44:45], 0, v[132:133]
	s_add_i32 m0, s54, 0xc000
	ds_read_b128 v[184:187], v167
	ds_read_b128 v[188:191], v167 offset:1024
	ds_read_b128 v[192:195], v167 offset:2048
	ds_read_b128 v[196:199], v167 offset:3072
	ds_read_b128 v[200:203], v167 offset:4096
	ds_read_b128 v[204:207], v167 offset:5120
	ds_read_b128 v[208:211], v167 offset:6144
	ds_read_b128 v[212:215], v167 offset:7168
	global_load_lds_dwordx4 v[160:161], off
	v_lshl_add_u64 v[160:161], s[44:45], 0, v[134:135]
	s_add_i32 m0, s54, 0xe000
	s_nop 0
	global_load_lds_dwordx4 v[160:161], off
	s_cmp_lt_u32 s32, 40
	s_cbranch_scc1 .Lrx_p5_0_8
	s_waitcnt vmcnt(40)
	s_branch .Lrx_p5_0_done

.Lrx_p5_0_done:
	s_waitcnt lgkmcnt(0)
	s_barrier
	s_setprio 1
	s_waitcnt lgkmcnt(0)
	v_mfma_f32_16x16x32_bf16 v[124:127], v[140:143], v[184:187], v[124:127]
	v_mfma_f32_16x16x32_bf16 v[120:123], v[148:151], v[184:187], v[120:123]
	v_mfma_f32_16x16x32_bf16 v[108:111], v[140:143], v[192:195], v[108:111]
	v_mfma_f32_16x16x32_bf16 v[104:107], v[148:151], v[192:195], v[104:107]
	v_mfma_f32_16x16x32_bf16 v[92:95], v[140:143], v[200:203], v[92:95]
	v_mfma_f32_16x16x32_bf16 v[88:91], v[148:151], v[200:203], v[88:91]
	v_mfma_f32_16x16x32_bf16 v[76:79], v[140:143], v[208:211], v[76:79]
	v_mfma_f32_16x16x32_bf16 v[72:75], v[148:151], v[208:211], v[72:75]
	v_mfma_f32_16x16x32_bf16 v[124:127], v[144:147], v[188:191], v[124:127]
	v_mfma_f32_16x16x32_bf16 v[120:123], v[152:155], v[188:191], v[120:123]
	v_mfma_f32_16x16x32_bf16 v[108:111], v[144:147], v[196:199], v[108:111]
	v_mfma_f32_16x16x32_bf16 v[104:107], v[152:155], v[196:199], v[104:107]
	v_mfma_f32_16x16x32_bf16 v[92:95], v[144:147], v[204:207], v[92:95]
	v_mfma_f32_16x16x32_bf16 v[88:91], v[152:155], v[204:207], v[88:91]
	v_mfma_f32_16x16x32_bf16 v[76:79], v[144:147], v[212:215], v[76:79]
	v_mfma_f32_16x16x32_bf16 v[72:75], v[152:155], v[212:215], v[72:75]
	s_setprio 0
	s_setprio 1
	v_mfma_f32_16x16x32_bf16 v[116:119], v[156:159], v[184:187], v[116:119]
	v_mfma_f32_16x16x32_bf16 v[112:115], v[176:179], v[184:187], v[112:115]
	v_mfma_f32_16x16x32_bf16 v[100:103], v[156:159], v[192:195], v[100:103]
	v_mfma_f32_16x16x32_bf16 v[96:99], v[176:179], v[192:195], v[96:99]
	v_mfma_f32_16x16x32_bf16 v[84:87], v[156:159], v[200:203], v[84:87]
	v_mfma_f32_16x16x32_bf16 v[80:83], v[176:179], v[200:203], v[80:83]
	v_mfma_f32_16x16x32_bf16 v[68:71], v[156:159], v[208:211], v[68:71]
	v_mfma_f32_16x16x32_bf16 v[64:67], v[176:179], v[208:211], v[64:67]
	v_mfma_f32_16x16x32_bf16 v[116:119], v[172:175], v[188:191], v[116:119]
	v_mfma_f32_16x16x32_bf16 v[112:115], v[180:183], v[188:191], v[112:115]
	v_mfma_f32_16x16x32_bf16 v[100:103], v[172:175], v[196:199], v[100:103]
	v_mfma_f32_16x16x32_bf16 v[96:99], v[180:183], v[196:199], v[96:99]
	v_mfma_f32_16x16x32_bf16 v[84:87], v[172:175], v[204:207], v[84:87]
	v_mfma_f32_16x16x32_bf16 v[80:83], v[180:183], v[204:207], v[80:83]
	v_mfma_f32_16x16x32_bf16 v[68:71], v[172:175], v[212:215], v[68:71]
	v_mfma_f32_16x16x32_bf16 v[64:67], v[180:183], v[212:215], v[64:67]
	s_setprio 0
	s_barrier
	s_add_i32 s72, s66, s53
	v_lshl_add_u64 v[160:161], s[46:47], 0, v[128:129]
	s_mov_b32 m0, s72
	ds_read_b128 v[184:187], v167 offset:16384
	ds_read_b128 v[188:191], v167 offset:17408
	ds_read_b128 v[192:195], v167 offset:18432
	ds_read_b128 v[196:199], v167 offset:19456
	ds_read_b128 v[200:203], v167 offset:20480
	ds_read_b128 v[204:207], v167 offset:21504
	ds_read_b128 v[208:211], v167 offset:22528
	ds_read_b128 v[212:215], v167 offset:23552
	global_load_lds_dwordx4 v[160:161], off
	s_add_i32 m0, s72, 0x2000
	s_add_u32 s72, s46, 0x80000
	v_lshl_add_u64 v[216:217], s[46:47], 0, v[130:131]
	s_addc_u32 s73, s47, 0
	s_add_i32 s74, s67, s53
	global_load_lds_dwordx4 v[216:217], off
	v_lshl_add_u64 v[218:219], s[72:73], 0, v[128:129]
	s_mov_b32 m0, s74
	v_lshl_add_u64 v[220:221], s[48:49], 0, v[130:131]
	global_load_lds_dwordx4 v[218:219], off
	v_lshl_add_u64 v[218:219], s[72:73], 0, v[130:131]
	s_add_i32 m0, s74, 0x2000
	s_nop 0
	global_load_lds_dwordx4 v[218:219], off
	v_lshl_add_u64 v[218:219], s[48:49], 0, v[128:129]
	s_mov_b32 m0, s54
	s_nop 0
	global_load_lds_dwordx4 v[218:219], off
	s_mov_b32 m0, s55
	s_nop 0
	global_load_lds_dwordx4 v[220:221], off
	s_cmp_lt_u32 s32, 40
	s_cbranch_scc1 .Lrx_p5_1_8
	s_waitcnt vmcnt(40)
	s_branch .Lrx_p5_1_done

.Lrx_p5_1_done:
	s_mov_b32 s32, 8
	s_waitcnt lgkmcnt(0)
	s_barrier
	s_setprio 1
	s_waitcnt lgkmcnt(0)
	v_mfma_f32_16x16x32_bf16 v[60:63], v[140:143], v[184:187], v[60:63]
	v_mfma_f32_16x16x32_bf16 v[56:59], v[148:151], v[184:187], v[56:59]
	v_mfma_f32_16x16x32_bf16 v[44:47], v[140:143], v[192:195], v[44:47]
	v_mfma_f32_16x16x32_bf16 v[40:43], v[148:151], v[192:195], v[40:43]
	v_mfma_f32_16x16x32_bf16 v[28:31], v[140:143], v[200:203], v[28:31]
	v_mfma_f32_16x16x32_bf16 v[24:27], v[148:151], v[200:203], v[24:27]
	v_mfma_f32_16x16x32_bf16 v[12:15], v[140:143], v[208:211], v[12:15]
	v_mfma_f32_16x16x32_bf16 v[8:11], v[148:151], v[208:211], v[8:11]
	v_mfma_f32_16x16x32_bf16 v[60:63], v[144:147], v[188:191], v[60:63]
	v_mfma_f32_16x16x32_bf16 v[56:59], v[152:155], v[188:191], v[56:59]
	v_mfma_f32_16x16x32_bf16 v[44:47], v[144:147], v[196:199], v[44:47]
	v_mfma_f32_16x16x32_bf16 v[40:43], v[152:155], v[196:199], v[40:43]
	v_mfma_f32_16x16x32_bf16 v[28:31], v[144:147], v[204:207], v[28:31]
	v_mfma_f32_16x16x32_bf16 v[24:27], v[152:155], v[204:207], v[24:27]
	v_mfma_f32_16x16x32_bf16 v[12:15], v[144:147], v[212:215], v[12:15]
	v_mfma_f32_16x16x32_bf16 v[8:11], v[152:155], v[212:215], v[8:11]
	s_setprio 0
	s_setprio 1
	v_mfma_f32_16x16x32_bf16 v[52:55], v[156:159], v[184:187], v[52:55]
	v_mfma_f32_16x16x32_bf16 v[48:51], v[176:179], v[184:187], v[48:51]
	v_mfma_f32_16x16x32_bf16 v[36:39], v[156:159], v[192:195], v[36:39]
	v_mfma_f32_16x16x32_bf16 v[32:35], v[176:179], v[192:195], v[32:35]
	v_mfma_f32_16x16x32_bf16 v[20:23], v[156:159], v[200:203], v[20:23]
	v_mfma_f32_16x16x32_bf16 v[16:19], v[176:179], v[200:203], v[16:19]
	v_mfma_f32_16x16x32_bf16 v[4:7], v[156:159], v[208:211], v[4:7]
	v_mfma_f32_16x16x32_bf16 v[0:3], v[176:179], v[208:211], v[0:3]
	v_mfma_f32_16x16x32_bf16 v[52:55], v[172:175], v[188:191], v[52:55]
	v_mfma_f32_16x16x32_bf16 v[48:51], v[180:183], v[188:191], v[48:51]
	v_mfma_f32_16x16x32_bf16 v[36:39], v[172:175], v[196:199], v[36:39]
	v_mfma_f32_16x16x32_bf16 v[32:35], v[180:183], v[196:199], v[32:35]
	v_mfma_f32_16x16x32_bf16 v[20:23], v[172:175], v[204:207], v[20:23]
	v_mfma_f32_16x16x32_bf16 v[16:19], v[180:183], v[204:207], v[16:19]
	v_mfma_f32_16x16x32_bf16 v[4:7], v[172:175], v[212:215], v[4:7]
	v_mfma_f32_16x16x32_bf16 v[0:3], v[180:183], v[212:215], v[0:3]
	s_setprio 0
	s_barrier
	s_add_i32 s72, 0, 0x18000
	s_add_i32 s73, 0, 0x1c000
	v_add_u32_e32 v152, s72, v163
	v_add_u32_e32 v171, s73, v163
	ds_read_b128 v[140:143], v152
	ds_read_b128 v[144:147], v152 offset:1024
	ds_read_b128 v[148:151], v152 offset:2048
	ds_read_b128 v[152:155], v152 offset:3072
	ds_read_b128 v[156:159], v171
	ds_read_b128 v[172:175], v171 offset:1024
	ds_read_b128 v[176:179], v171 offset:2048
	ds_read_b128 v[180:183], v171 offset:3072
	s_add_u32 s48, s48, 0x80000
	s_addc_u32 s49, s49, 0
	s_mov_b32 m0, s56
	v_lshl_add_u64 v[222:223], s[48:49], 0, v[128:129]
	ds_read_b128 v[184:187], v167 offset:32768
	ds_read_b128 v[188:191], v167 offset:33792
	ds_read_b128 v[192:195], v167 offset:34816
	ds_read_b128 v[196:199], v167 offset:35840
	ds_read_b128 v[200:203], v167 offset:36864
	ds_read_b128 v[204:207], v167 offset:37888
	ds_read_b128 v[208:211], v167 offset:38912
	ds_read_b128 v[212:215], v167 offset:39936
	global_load_lds_dwordx4 v[222:223], off
	v_lshl_add_u64 v[222:223], s[48:49], 0, v[130:131]
	s_mov_b32 m0, s57
	s_nop 0
	global_load_lds_dwordx4 v[222:223], off
	s_waitcnt vmcnt(8)
	s_waitcnt lgkmcnt(0)
	s_barrier
	s_setprio 1
	s_waitcnt lgkmcnt(0)
	v_mfma_f32_16x16x32_bf16 v[124:127], v[140:143], v[184:187], v[124:127]
	v_mfma_f32_16x16x32_bf16 v[120:123], v[148:151], v[184:187], v[120:123]
	v_mfma_f32_16x16x32_bf16 v[108:111], v[140:143], v[192:195], v[108:111]
	v_mfma_f32_16x16x32_bf16 v[104:107], v[148:151], v[192:195], v[104:107]
	v_mfma_f32_16x16x32_bf16 v[92:95], v[140:143], v[200:203], v[92:95]
	v_mfma_f32_16x16x32_bf16 v[88:91], v[148:151], v[200:203], v[88:91]
	v_mfma_f32_16x16x32_bf16 v[76:79], v[140:143], v[208:211], v[76:79]
	v_mfma_f32_16x16x32_bf16 v[72:75], v[148:151], v[208:211], v[72:75]
	v_mfma_f32_16x16x32_bf16 v[124:127], v[144:147], v[188:191], v[124:127]
	v_mfma_f32_16x16x32_bf16 v[120:123], v[152:155], v[188:191], v[120:123]
	v_mfma_f32_16x16x32_bf16 v[108:111], v[144:147], v[196:199], v[108:111]
	v_mfma_f32_16x16x32_bf16 v[104:107], v[152:155], v[196:199], v[104:107]
	v_mfma_f32_16x16x32_bf16 v[92:95], v[144:147], v[204:207], v[92:95]
	v_mfma_f32_16x16x32_bf16 v[88:91], v[152:155], v[204:207], v[88:91]
	v_mfma_f32_16x16x32_bf16 v[76:79], v[144:147], v[212:215], v[76:79]
	v_mfma_f32_16x16x32_bf16 v[72:75], v[152:155], v[212:215], v[72:75]
	s_setprio 0
	s_setprio 1
	v_mfma_f32_16x16x32_bf16 v[116:119], v[156:159], v[184:187], v[116:119]
	v_mfma_f32_16x16x32_bf16 v[112:115], v[176:179], v[184:187], v[112:115]
	v_mfma_f32_16x16x32_bf16 v[100:103], v[156:159], v[192:195], v[100:103]
	v_mfma_f32_16x16x32_bf16 v[96:99], v[176:179], v[192:195], v[96:99]
	v_mfma_f32_16x16x32_bf16 v[84:87], v[156:159], v[200:203], v[84:87]
	v_mfma_f32_16x16x32_bf16 v[80:83], v[176:179], v[200:203], v[80:83]
	v_mfma_f32_16x16x32_bf16 v[68:71], v[156:159], v[208:211], v[68:71]
	v_mfma_f32_16x16x32_bf16 v[64:67], v[176:179], v[208:211], v[64:67]
	v_mfma_f32_16x16x32_bf16 v[116:119], v[172:175], v[188:191], v[116:119]
	v_mfma_f32_16x16x32_bf16 v[112:115], v[180:183], v[188:191], v[112:115]
	v_mfma_f32_16x16x32_bf16 v[100:103], v[172:175], v[196:199], v[100:103]
	v_mfma_f32_16x16x32_bf16 v[96:99], v[180:183], v[196:199], v[96:99]
	v_mfma_f32_16x16x32_bf16 v[84:87], v[172:175], v[204:207], v[84:87]
	v_mfma_f32_16x16x32_bf16 v[80:83], v[180:183], v[204:207], v[80:83]
	v_mfma_f32_16x16x32_bf16 v[68:71], v[172:175], v[212:215], v[68:71]
	v_mfma_f32_16x16x32_bf16 v[64:67], v[180:183], v[212:215], v[64:67]
	s_setprio 0
	s_barrier
	s_add_i32 s48, s72, s53
	v_lshl_add_u64 v[160:161], v[160:161], 0, s[22:23]
	s_mov_b32 m0, s48
	ds_read_b128 v[184:187], v167 offset:49152
	ds_read_b128 v[188:191], v167 offset:50176
	ds_read_b128 v[192:195], v167 offset:51200
	ds_read_b128 v[196:199], v167 offset:52224
	ds_read_b128 v[200:203], v167 offset:53248
	ds_read_b128 v[204:207], v167 offset:54272
	ds_read_b128 v[208:211], v167 offset:55296
	ds_read_b128 v[212:215], v167 offset:56320
	global_load_lds_dwordx4 v[160:161], off
	s_add_i32 m0, s48, 0x2000
	s_add_u32 s46, s46, 0x80080
	v_lshl_add_u64 v[160:161], v[216:217], 0, s[22:23]
	s_addc_u32 s47, s47, 0
	s_add_i32 s48, s73, s53
	global_load_lds_dwordx4 v[160:161], off
	v_lshl_add_u64 v[160:161], s[46:47], 0, v[128:129]
	s_mov_b32 m0, s48
	s_nop 0
	global_load_lds_dwordx4 v[160:161], off
	v_lshl_add_u64 v[160:161], s[46:47], 0, v[130:131]
	s_add_i32 m0, s48, 0x2000
	s_nop 0
	global_load_lds_dwordx4 v[160:161], off
	v_lshl_add_u64 v[160:161], v[218:219], 0, s[22:23]
	s_mov_b32 m0, s60
	s_nop 0
	global_load_lds_dwordx4 v[160:161], off
	v_lshl_add_u64 v[160:161], v[220:221], 0, s[22:23]
	s_mov_b32 m0, s61
	s_nop 0
	global_load_lds_dwordx4 v[160:161], off
	s_waitcnt vmcnt(8)
	s_waitcnt lgkmcnt(0)
	s_barrier
	s_setprio 1
	s_waitcnt lgkmcnt(0)
	v_mfma_f32_16x16x32_bf16 v[60:63], v[140:143], v[184:187], v[60:63]
	v_mfma_f32_16x16x32_bf16 v[56:59], v[148:151], v[184:187], v[56:59]
	v_mfma_f32_16x16x32_bf16 v[44:47], v[140:143], v[192:195], v[44:47]
	v_mfma_f32_16x16x32_bf16 v[40:43], v[148:151], v[192:195], v[40:43]
	v_mfma_f32_16x16x32_bf16 v[28:31], v[140:143], v[200:203], v[28:31]
	v_mfma_f32_16x16x32_bf16 v[24:27], v[148:151], v[200:203], v[24:27]
	v_mfma_f32_16x16x32_bf16 v[12:15], v[140:143], v[208:211], v[12:15]
	v_mfma_f32_16x16x32_bf16 v[8:11], v[148:151], v[208:211], v[8:11]
	v_mfma_f32_16x16x32_bf16 v[60:63], v[144:147], v[188:191], v[60:63]
	v_mfma_f32_16x16x32_bf16 v[56:59], v[152:155], v[188:191], v[56:59]
	v_mfma_f32_16x16x32_bf16 v[44:47], v[144:147], v[196:199], v[44:47]
	v_mfma_f32_16x16x32_bf16 v[40:43], v[152:155], v[196:199], v[40:43]
	v_mfma_f32_16x16x32_bf16 v[28:31], v[144:147], v[204:207], v[28:31]
	v_mfma_f32_16x16x32_bf16 v[24:27], v[152:155], v[204:207], v[24:27]
	v_mfma_f32_16x16x32_bf16 v[12:15], v[144:147], v[212:215], v[12:15]
	v_mfma_f32_16x16x32_bf16 v[8:11], v[152:155], v[212:215], v[8:11]
	s_setprio 0
	s_setprio 1
	v_mfma_f32_16x16x32_bf16 v[52:55], v[156:159], v[184:187], v[52:55]
	v_mfma_f32_16x16x32_bf16 v[48:51], v[176:179], v[184:187], v[48:51]
	v_mfma_f32_16x16x32_bf16 v[36:39], v[156:159], v[192:195], v[36:39]
	v_mfma_f32_16x16x32_bf16 v[32:35], v[176:179], v[192:195], v[32:35]
	v_mfma_f32_16x16x32_bf16 v[20:23], v[156:159], v[200:203], v[20:23]
	v_mfma_f32_16x16x32_bf16 v[16:19], v[176:179], v[200:203], v[16:19]
	v_mfma_f32_16x16x32_bf16 v[4:7], v[156:159], v[208:211], v[4:7]
	v_mfma_f32_16x16x32_bf16 v[0:3], v[176:179], v[208:211], v[0:3]
	v_mfma_f32_16x16x32_bf16 v[52:55], v[172:175], v[188:191], v[52:55]
	v_mfma_f32_16x16x32_bf16 v[48:51], v[180:183], v[188:191], v[48:51]
	v_mfma_f32_16x16x32_bf16 v[36:39], v[172:175], v[196:199], v[36:39]
	v_mfma_f32_16x16x32_bf16 v[32:35], v[180:183], v[196:199], v[32:35]
	v_mfma_f32_16x16x32_bf16 v[20:23], v[172:175], v[204:207], v[20:23]
	v_mfma_f32_16x16x32_bf16 v[16:19], v[180:183], v[204:207], v[16:19]
	v_mfma_f32_16x16x32_bf16 v[4:7], v[172:175], v[212:215], v[4:7]
	v_mfma_f32_16x16x32_bf16 v[0:3], v[180:183], v[212:215], v[0:3]
	s_setprio 0
	s_barrier
	s_add_i32 s71, s71, 2
	s_add_u32 s44, s44, 0x100
	s_addc_u32 s45, s45, 0
	s_add_u32 s69, s69, 0x100
	s_addc_u32 s70, s70, 0
	s_cmp_gt_u32 s71, 29
	s_cbranch_scc0 .LBB0_485
	s_and_b64 vcc, exec, s[24:25]
	s_cbranch_vccz .LBB0_488
	s_barrier

.LBB0_515:
	global_load_dword v192, v141, s[10:11] sc1
	global_load_dword v193, v141, s[10:11] offset:64 sc1
	global_load_dword v194, v141, s[10:11] offset:128 sc1
	global_load_dword v195, v141, s[10:11] offset:192 sc1
	global_load_dword v196, v141, s[10:11] offset:512 sc1
	global_load_dword v197, v141, s[10:11] offset:576 sc1
	global_load_dword v198, v141, s[10:11] offset:640 sc1
	global_load_dword v199, v141, s[10:11] offset:704 sc1
	s_waitcnt vmcnt(0)
	v_fmamk_f32 v192, v192, 0x3a800000, v169
	v_mul_f32_e32 v200, 0x4f800000, v192
	v_cmp_gt_f32_e32 vcc, s68, v192
	s_nop 1
	v_cndmask_b32_e32 v192, v192, v200, vcc
	v_sqrt_f32_e32 v200, v192
	s_nop 0
	v_add_u32_e32 v201, -1, v200
	v_add_u32_e32 v202, 1, v200
	v_fma_f32 v203, -v201, v200, v192
	v_fma_f32 v204, -v202, v200, v192
	v_cmp_ge_f32_e64 s[8:9], 0, v203
	s_nop 1
	v_cndmask_b32_e64 v200, v200, v201, s[8:9]
	v_cmp_lt_f32_e64 s[8:9], 0, v204
	s_nop 1
	v_cndmask_b32_e64 v200, v200, v202, s[8:9]
	v_mul_f32_e32 v201, 0x37800000, v200
	v_cndmask_b32_e32 v200, v200, v201, vcc
	v_cmp_class_f32_e32 vcc, v192, v170
	s_nop 1
	v_cndmask_b32_e32 v192, v200, v192, vcc
	v_div_scale_f32 v202, s[8:9], v192, v192, 1.0
	v_rcp_f32_e32 v203, v202
	v_div_scale_f32 v200, vcc, 1.0, v192, 1.0
	v_fma_f32 v201, -v202, v203, 1.0
	v_fmac_f32_e32 v203, v201, v203
	v_mul_f32_e32 v201, v200, v203
	v_fma_f32 v204, -v202, v201, v200
	v_fmac_f32_e32 v201, v204, v203
	v_fma_f32 v200, -v202, v201, v200
	v_div_fmas_f32 v200, v200, v203, v201
	v_div_fixup_f32 v206, v200, v192, 1.0
	v_pk_mul_f32 v[124:125], v[124:125], v[206:207] op_sel_hi:[1,0]
	v_pk_mul_f32 v[126:127], v[126:127], v[206:207] op_sel_hi:[1,0]
	v_pk_mul_f32 v[124:125], v[176:177], v[124:125]
	v_pk_mul_f32 v[126:127], v[178:179], v[126:127]
	v_pk_mul_f32 v[120:121], v[120:121], v[206:207] op_sel_hi:[1,0]
	v_pk_mul_f32 v[122:123], v[122:123], v[206:207] op_sel_hi:[1,0]
	v_pk_mul_f32 v[120:121], v[180:181], v[120:121]
	v_pk_mul_f32 v[122:123], v[182:183], v[122:123]
	v_pk_mul_f32 v[116:117], v[116:117], v[206:207] op_sel_hi:[1,0]
	v_pk_mul_f32 v[118:119], v[118:119], v[206:207] op_sel_hi:[1,0]
	v_pk_mul_f32 v[116:117], v[184:185], v[116:117]
	v_pk_mul_f32 v[118:119], v[186:187], v[118:119]
	v_pk_mul_f32 v[112:113], v[112:113], v[206:207] op_sel_hi:[1,0]
	v_pk_mul_f32 v[114:115], v[114:115], v[206:207] op_sel_hi:[1,0]
	v_pk_mul_f32 v[112:113], v[188:189], v[112:113]
	v_pk_mul_f32 v[114:115], v[190:191], v[114:115]
	ds_write_b128 v171, v[124:127]
	ds_write_b128 v171, v[120:123] offset:64
	ds_read_b128 v[124:127], v172
	ds_read_b128 v[120:123], v172 offset:1152
	ds_write_b128 v171, v[116:119]
	ds_write_b128 v171, v[112:115] offset:64
	ds_read_b128 v[116:119], v172
	ds_read_b128 v[112:115], v172 offset:1152
	s_add_u32 s100, s14, 0x0
	s_addc_u32 s101, s15, 0
	s_add_u32 s44, s14, 0x8000
	s_addc_u32 s45, s15, 0
	s_waitcnt lgkmcnt(4)
	global_store_dwordx4 v142, v[124:127], s[100:101] nt
	global_store_dwordx4 v142, v[120:123], s[44:45] nt
	s_waitcnt lgkmcnt(0)
	global_store_dwordx4 v142, v[116:119], s[100:101] offset:512 nt
	global_store_dwordx4 v142, v[112:115], s[44:45] offset:512 nt
	v_fmamk_f32 v193, v193, 0x3a800000, v169
	v_mul_f32_e32 v200, 0x4f800000, v193
	v_cmp_gt_f32_e32 vcc, s68, v193
	s_nop 1
	v_cndmask_b32_e32 v193, v193, v200, vcc
	v_sqrt_f32_e32 v200, v193
	s_nop 0
	v_add_u32_e32 v201, -1, v200
	v_add_u32_e32 v202, 1, v200
	v_fma_f32 v203, -v201, v200, v193
	v_fma_f32 v204, -v202, v200, v193
	v_cmp_ge_f32_e64 s[8:9], 0, v203
	s_nop 1
	v_cndmask_b32_e64 v200, v200, v201, s[8:9]
	v_cmp_lt_f32_e64 s[8:9], 0, v204
	s_nop 1
	v_cndmask_b32_e64 v200, v200, v202, s[8:9]
	v_mul_f32_e32 v201, 0x37800000, v200
	v_cndmask_b32_e32 v200, v200, v201, vcc
	v_cmp_class_f32_e32 vcc, v193, v170
	s_nop 1
	v_cndmask_b32_e32 v193, v200, v193, vcc
	v_div_scale_f32 v202, s[8:9], v193, v193, 1.0
	v_rcp_f32_e32 v203, v202
	v_div_scale_f32 v200, vcc, 1.0, v193, 1.0
	v_fma_f32 v201, -v202, v203, 1.0
	v_fmac_f32_e32 v203, v201, v203
	v_mul_f32_e32 v201, v200, v203
	v_fma_f32 v204, -v202, v201, v200
	v_fmac_f32_e32 v201, v204, v203
	v_fma_f32 v200, -v202, v201, v200
	v_div_fmas_f32 v200, v200, v203, v201
	v_div_fixup_f32 v206, v200, v193, 1.0
	v_pk_mul_f32 v[108:109], v[108:109], v[206:207] op_sel_hi:[1,0]
	v_pk_mul_f32 v[110:111], v[110:111], v[206:207] op_sel_hi:[1,0]
	v_pk_mul_f32 v[108:109], v[176:177], v[108:109]
	v_pk_mul_f32 v[110:111], v[178:179], v[110:111]
	v_pk_mul_f32 v[104:105], v[104:105], v[206:207] op_sel_hi:[1,0]
	v_pk_mul_f32 v[106:107], v[106:107], v[206:207] op_sel_hi:[1,0]
	v_pk_mul_f32 v[104:105], v[180:181], v[104:105]
	v_pk_mul_f32 v[106:107], v[182:183], v[106:107]
	v_pk_mul_f32 v[100:101], v[100:101], v[206:207] op_sel_hi:[1,0]
	v_pk_mul_f32 v[102:103], v[102:103], v[206:207] op_sel_hi:[1,0]
	v_pk_mul_f32 v[100:101], v[184:185], v[100:101]
	v_pk_mul_f32 v[102:103], v[186:187], v[102:103]
	v_pk_mul_f32 v[96:97], v[96:97], v[206:207] op_sel_hi:[1,0]
	v_pk_mul_f32 v[98:99], v[98:99], v[206:207] op_sel_hi:[1,0]
	v_pk_mul_f32 v[96:97], v[188:189], v[96:97]
	v_pk_mul_f32 v[98:99], v[190:191], v[98:99]
	ds_write_b128 v171, v[108:111]
	ds_write_b128 v171, v[104:107] offset:64
	ds_read_b128 v[108:111], v172
	ds_read_b128 v[104:107], v172 offset:1152
	ds_write_b128 v171, v[100:103]
	ds_write_b128 v171, v[96:99] offset:64
	ds_read_b128 v[100:103], v172
	ds_read_b128 v[96:99], v172 offset:1152
	s_add_u32 s100, s14, 0x10000
	s_addc_u32 s101, s15, 0
	s_add_u32 s44, s14, 0x18000
	s_addc_u32 s45, s15, 0
	s_waitcnt lgkmcnt(4)
	global_store_dwordx4 v142, v[108:111], s[100:101] nt
	global_store_dwordx4 v142, v[104:107], s[44:45] nt
	s_waitcnt lgkmcnt(0)
	global_store_dwordx4 v142, v[100:103], s[100:101] offset:512 nt
	global_store_dwordx4 v142, v[96:99], s[44:45] offset:512 nt
	v_fmamk_f32 v194, v194, 0x3a800000, v169
	v_mul_f32_e32 v200, 0x4f800000, v194
	v_cmp_gt_f32_e32 vcc, s68, v194
	s_nop 1
	v_cndmask_b32_e32 v194, v194, v200, vcc
	v_sqrt_f32_e32 v200, v194
	s_nop 0
	v_add_u32_e32 v201, -1, v200
	v_add_u32_e32 v202, 1, v200
	v_fma_f32 v203, -v201, v200, v194
	v_fma_f32 v204, -v202, v200, v194
	v_cmp_ge_f32_e64 s[8:9], 0, v203
	s_nop 1
	v_cndmask_b32_e64 v200, v200, v201, s[8:9]
	v_cmp_lt_f32_e64 s[8:9], 0, v204
	s_nop 1
	v_cndmask_b32_e64 v200, v200, v202, s[8:9]
	v_mul_f32_e32 v201, 0x37800000, v200
	v_cndmask_b32_e32 v200, v200, v201, vcc
	v_cmp_class_f32_e32 vcc, v194, v170
	s_nop 1
	v_cndmask_b32_e32 v194, v200, v194, vcc
	v_div_scale_f32 v202, s[8:9], v194, v194, 1.0
	v_rcp_f32_e32 v203, v202
	v_div_scale_f32 v200, vcc, 1.0, v194, 1.0
	v_fma_f32 v201, -v202, v203, 1.0
	v_fmac_f32_e32 v203, v201, v203
	v_mul_f32_e32 v201, v200, v203
	v_fma_f32 v204, -v202, v201, v200
	v_fmac_f32_e32 v201, v204, v203
	v_fma_f32 v200, -v202, v201, v200
	v_div_fmas_f32 v200, v200, v203, v201
	v_div_fixup_f32 v206, v200, v194, 1.0
	v_pk_mul_f32 v[92:93], v[92:93], v[206:207] op_sel_hi:[1,0]
	v_pk_mul_f32 v[94:95], v[94:95], v[206:207] op_sel_hi:[1,0]
	v_pk_mul_f32 v[92:93], v[176:177], v[92:93]
	v_pk_mul_f32 v[94:95], v[178:179], v[94:95]
	v_pk_mul_f32 v[88:89], v[88:89], v[206:207] op_sel_hi:[1,0]
	v_pk_mul_f32 v[90:91], v[90:91], v[206:207] op_sel_hi:[1,0]
	v_pk_mul_f32 v[88:89], v[180:181], v[88:89]
	v_pk_mul_f32 v[90:91], v[182:183], v[90:91]
	v_pk_mul_f32 v[84:85], v[84:85], v[206:207] op_sel_hi:[1,0]
	v_pk_mul_f32 v[86:87], v[86:87], v[206:207] op_sel_hi:[1,0]
	v_pk_mul_f32 v[84:85], v[184:185], v[84:85]
	v_pk_mul_f32 v[86:87], v[186:187], v[86:87]
	v_pk_mul_f32 v[80:81], v[80:81], v[206:207] op_sel_hi:[1,0]
	v_pk_mul_f32 v[82:83], v[82:83], v[206:207] op_sel_hi:[1,0]
	v_pk_mul_f32 v[80:81], v[188:189], v[80:81]
	v_pk_mul_f32 v[82:83], v[190:191], v[82:83]
	ds_write_b128 v171, v[92:95]
	ds_write_b128 v171, v[88:91] offset:64
	ds_read_b128 v[92:95], v172
	ds_read_b128 v[88:91], v172 offset:1152
	ds_write_b128 v171, v[84:87]
	ds_write_b128 v171, v[80:83] offset:64
	ds_read_b128 v[84:87], v172
	ds_read_b128 v[80:83], v172 offset:1152
	s_add_u32 s100, s14, 0x20000
	s_addc_u32 s101, s15, 0
	s_add_u32 s44, s14, 0x28000
	s_addc_u32 s45, s15, 0
	s_waitcnt lgkmcnt(4)
	global_store_dwordx4 v142, v[92:95], s[100:101] nt
	global_store_dwordx4 v142, v[88:91], s[44:45] nt
	s_waitcnt lgkmcnt(0)
	global_store_dwordx4 v142, v[84:87], s[100:101] offset:512 nt
	global_store_dwordx4 v142, v[80:83], s[44:45] offset:512 nt
	v_fmamk_f32 v195, v195, 0x3a800000, v169
	v_mul_f32_e32 v200, 0x4f800000, v195
	v_cmp_gt_f32_e32 vcc, s68, v195
	s_nop 1
	v_cndmask_b32_e32 v195, v195, v200, vcc
	v_sqrt_f32_e32 v200, v195
	s_nop 0
	v_add_u32_e32 v201, -1, v200
	v_add_u32_e32 v202, 1, v200
	v_fma_f32 v203, -v201, v200, v195
	v_fma_f32 v204, -v202, v200, v195
	v_cmp_ge_f32_e64 s[8:9], 0, v203
	s_nop 1
	v_cndmask_b32_e64 v200, v200, v201, s[8:9]
	v_cmp_lt_f32_e64 s[8:9], 0, v204
	s_nop 1
	v_cndmask_b32_e64 v200, v200, v202, s[8:9]
	v_mul_f32_e32 v201, 0x37800000, v200
	v_cndmask_b32_e32 v200, v200, v201, vcc
	v_cmp_class_f32_e32 vcc, v195, v170
	s_nop 1
	v_cndmask_b32_e32 v195, v200, v195, vcc
	v_div_scale_f32 v202, s[8:9], v195, v195, 1.0
	v_rcp_f32_e32 v203, v202
	v_div_scale_f32 v200, vcc, 1.0, v195, 1.0
	v_fma_f32 v201, -v202, v203, 1.0
	v_fmac_f32_e32 v203, v201, v203
	v_mul_f32_e32 v201, v200, v203
	v_fma_f32 v204, -v202, v201, v200
	v_fmac_f32_e32 v201, v204, v203
	v_fma_f32 v200, -v202, v201, v200
	v_div_fmas_f32 v200, v200, v203, v201
	v_div_fixup_f32 v206, v200, v195, 1.0
	v_pk_mul_f32 v[76:77], v[76:77], v[206:207] op_sel_hi:[1,0]
	v_pk_mul_f32 v[78:79], v[78:79], v[206:207] op_sel_hi:[1,0]
	v_pk_mul_f32 v[76:77], v[176:177], v[76:77]
	v_pk_mul_f32 v[78:79], v[178:179], v[78:79]
	v_pk_mul_f32 v[72:73], v[72:73], v[206:207] op_sel_hi:[1,0]
	v_pk_mul_f32 v[74:75], v[74:75], v[206:207] op_sel_hi:[1,0]
	v_pk_mul_f32 v[72:73], v[180:181], v[72:73]
	v_pk_mul_f32 v[74:75], v[182:183], v[74:75]
	v_pk_mul_f32 v[68:69], v[68:69], v[206:207] op_sel_hi:[1,0]
	v_pk_mul_f32 v[70:71], v[70:71], v[206:207] op_sel_hi:[1,0]
	v_pk_mul_f32 v[68:69], v[184:185], v[68:69]
	v_pk_mul_f32 v[70:71], v[186:187], v[70:71]
	v_pk_mul_f32 v[64:65], v[64:65], v[206:207] op_sel_hi:[1,0]
	v_pk_mul_f32 v[66:67], v[66:67], v[206:207] op_sel_hi:[1,0]
	v_pk_mul_f32 v[64:65], v[188:189], v[64:65]
	v_pk_mul_f32 v[66:67], v[190:191], v[66:67]
	ds_write_b128 v171, v[76:79]
	ds_write_b128 v171, v[72:75] offset:64
	ds_read_b128 v[76:79], v172
	ds_read_b128 v[72:75], v172 offset:1152
	ds_write_b128 v171, v[68:71]
	ds_write_b128 v171, v[64:67] offset:64
	ds_read_b128 v[68:71], v172
	ds_read_b128 v[64:67], v172 offset:1152
	s_add_u32 s100, s14, 0x30000
	s_addc_u32 s101, s15, 0
	s_add_u32 s44, s14, 0x38000
	s_addc_u32 s45, s15, 0
	s_waitcnt lgkmcnt(4)
	global_store_dwordx4 v142, v[76:79], s[100:101] nt
	global_store_dwordx4 v142, v[72:75], s[44:45] nt
	s_waitcnt lgkmcnt(0)
	global_store_dwordx4 v142, v[68:71], s[100:101] offset:512 nt
	global_store_dwordx4 v142, v[64:67], s[44:45] offset:512 nt
	v_fmamk_f32 v196, v196, 0x3a800000, v169
	v_mul_f32_e32 v200, 0x4f800000, v196
	v_cmp_gt_f32_e32 vcc, s68, v196
	s_nop 1
	v_cndmask_b32_e32 v196, v196, v200, vcc
	v_sqrt_f32_e32 v200, v196
	s_nop 0
	v_add_u32_e32 v201, -1, v200
	v_add_u32_e32 v202, 1, v200
	v_fma_f32 v203, -v201, v200, v196
	v_fma_f32 v204, -v202, v200, v196
	v_cmp_ge_f32_e64 s[8:9], 0, v203
	s_nop 1
	v_cndmask_b32_e64 v200, v200, v201, s[8:9]
	v_cmp_lt_f32_e64 s[8:9], 0, v204
	s_nop 1
	v_cndmask_b32_e64 v200, v200, v202, s[8:9]
	v_mul_f32_e32 v201, 0x37800000, v200
	v_cndmask_b32_e32 v200, v200, v201, vcc
	v_cmp_class_f32_e32 vcc, v196, v170
	s_nop 1
	v_cndmask_b32_e32 v196, v200, v196, vcc
	v_div_scale_f32 v202, s[8:9], v196, v196, 1.0
	v_rcp_f32_e32 v203, v202
	v_div_scale_f32 v200, vcc, 1.0, v196, 1.0
	v_fma_f32 v201, -v202, v203, 1.0
	v_fmac_f32_e32 v203, v201, v203
	v_mul_f32_e32 v201, v200, v203
	v_fma_f32 v204, -v202, v201, v200
	v_fmac_f32_e32 v201, v204, v203
	v_fma_f32 v200, -v202, v201, v200
	v_div_fmas_f32 v200, v200, v203, v201
	v_div_fixup_f32 v206, v200, v196, 1.0
	v_pk_mul_f32 v[60:61], v[60:61], v[206:207] op_sel_hi:[1,0]
	v_pk_mul_f32 v[62:63], v[62:63], v[206:207] op_sel_hi:[1,0]
	v_pk_mul_f32 v[60:61], v[176:177], v[60:61]
	v_pk_mul_f32 v[62:63], v[178:179], v[62:63]
	v_pk_mul_f32 v[56:57], v[56:57], v[206:207] op_sel_hi:[1,0]
	v_pk_mul_f32 v[58:59], v[58:59], v[206:207] op_sel_hi:[1,0]
	v_pk_mul_f32 v[56:57], v[180:181], v[56:57]
	v_pk_mul_f32 v[58:59], v[182:183], v[58:59]
	v_pk_mul_f32 v[52:53], v[52:53], v[206:207] op_sel_hi:[1,0]
	v_pk_mul_f32 v[54:55], v[54:55], v[206:207] op_sel_hi:[1,0]
	v_pk_mul_f32 v[52:53], v[184:185], v[52:53]
	v_pk_mul_f32 v[54:55], v[186:187], v[54:55]
	v_pk_mul_f32 v[48:49], v[48:49], v[206:207] op_sel_hi:[1,0]
	v_pk_mul_f32 v[50:51], v[50:51], v[206:207] op_sel_hi:[1,0]
	v_pk_mul_f32 v[48:49], v[188:189], v[48:49]
	v_pk_mul_f32 v[50:51], v[190:191], v[50:51]
	ds_write_b128 v171, v[60:63]
	ds_write_b128 v171, v[56:59] offset:64
	ds_read_b128 v[60:63], v172
	ds_read_b128 v[56:59], v172 offset:1152
	ds_write_b128 v171, v[52:55]
	ds_write_b128 v171, v[48:51] offset:64
	ds_read_b128 v[52:55], v172
	ds_read_b128 v[48:51], v172 offset:1152
	s_add_u32 s100, s14, 0x80000
	s_addc_u32 s101, s15, 0
	s_add_u32 s44, s14, 0x88000
	s_addc_u32 s45, s15, 0
	s_waitcnt lgkmcnt(4)
	global_store_dwordx4 v142, v[60:63], s[100:101] nt
	global_store_dwordx4 v142, v[56:59], s[44:45] nt
	s_waitcnt lgkmcnt(0)
	global_store_dwordx4 v142, v[52:55], s[100:101] offset:512 nt
	global_store_dwordx4 v142, v[48:51], s[44:45] offset:512 nt
	v_fmamk_f32 v197, v197, 0x3a800000, v169
	v_mul_f32_e32 v200, 0x4f800000, v197
	v_cmp_gt_f32_e32 vcc, s68, v197
	s_nop 1
	v_cndmask_b32_e32 v197, v197, v200, vcc
	v_sqrt_f32_e32 v200, v197
	s_nop 0
	v_add_u32_e32 v201, -1, v200
	v_add_u32_e32 v202, 1, v200
	v_fma_f32 v203, -v201, v200, v197
	v_fma_f32 v204, -v202, v200, v197
	v_cmp_ge_f32_e64 s[8:9], 0, v203
	s_nop 1
	v_cndmask_b32_e64 v200, v200, v201, s[8:9]
	v_cmp_lt_f32_e64 s[8:9], 0, v204
	s_nop 1
	v_cndmask_b32_e64 v200, v200, v202, s[8:9]
	v_mul_f32_e32 v201, 0x37800000, v200
	v_cndmask_b32_e32 v200, v200, v201, vcc
	v_cmp_class_f32_e32 vcc, v197, v170
	s_nop 1
	v_cndmask_b32_e32 v197, v200, v197, vcc
	v_div_scale_f32 v202, s[8:9], v197, v197, 1.0
	v_rcp_f32_e32 v203, v202
	v_div_scale_f32 v200, vcc, 1.0, v197, 1.0
	v_fma_f32 v201, -v202, v203, 1.0
	v_fmac_f32_e32 v203, v201, v203
	v_mul_f32_e32 v201, v200, v203
	v_fma_f32 v204, -v202, v201, v200
	v_fmac_f32_e32 v201, v204, v203
	v_fma_f32 v200, -v202, v201, v200
	v_div_fmas_f32 v200, v200, v203, v201
	v_div_fixup_f32 v206, v200, v197, 1.0
	v_pk_mul_f32 v[44:45], v[44:45], v[206:207] op_sel_hi:[1,0]
	v_pk_mul_f32 v[46:47], v[46:47], v[206:207] op_sel_hi:[1,0]
	v_pk_mul_f32 v[44:45], v[176:177], v[44:45]
	v_pk_mul_f32 v[46:47], v[178:179], v[46:47]
	v_pk_mul_f32 v[40:41], v[40:41], v[206:207] op_sel_hi:[1,0]
	v_pk_mul_f32 v[42:43], v[42:43], v[206:207] op_sel_hi:[1,0]
	v_pk_mul_f32 v[40:41], v[180:181], v[40:41]
	v_pk_mul_f32 v[42:43], v[182:183], v[42:43]
	v_pk_mul_f32 v[36:37], v[36:37], v[206:207] op_sel_hi:[1,0]
	v_pk_mul_f32 v[38:39], v[38:39], v[206:207] op_sel_hi:[1,0]
	v_pk_mul_f32 v[36:37], v[184:185], v[36:37]
	v_pk_mul_f32 v[38:39], v[186:187], v[38:39]
	v_pk_mul_f32 v[32:33], v[32:33], v[206:207] op_sel_hi:[1,0]
	v_pk_mul_f32 v[34:35], v[34:35], v[206:207] op_sel_hi:[1,0]
	v_pk_mul_f32 v[32:33], v[188:189], v[32:33]
	v_pk_mul_f32 v[34:35], v[190:191], v[34:35]
	ds_write_b128 v171, v[44:47]
	ds_write_b128 v171, v[40:43] offset:64
	ds_read_b128 v[44:47], v172
	ds_read_b128 v[40:43], v172 offset:1152
	ds_write_b128 v171, v[36:39]
	ds_write_b128 v171, v[32:35] offset:64
	ds_read_b128 v[36:39], v172
	ds_read_b128 v[32:35], v172 offset:1152
	s_add_u32 s100, s14, 0x90000
	s_addc_u32 s101, s15, 0
	s_add_u32 s44, s14, 0x98000
	s_addc_u32 s45, s15, 0
	s_waitcnt lgkmcnt(4)
	global_store_dwordx4 v142, v[44:47], s[100:101] nt
	global_store_dwordx4 v142, v[40:43], s[44:45] nt
	s_waitcnt lgkmcnt(0)
	global_store_dwordx4 v142, v[36:39], s[100:101] offset:512 nt
	global_store_dwordx4 v142, v[32:35], s[44:45] offset:512 nt
	v_fmamk_f32 v198, v198, 0x3a800000, v169
	v_mul_f32_e32 v200, 0x4f800000, v198
	v_cmp_gt_f32_e32 vcc, s68, v198
	s_nop 1
	v_cndmask_b32_e32 v198, v198, v200, vcc
	v_sqrt_f32_e32 v200, v198
	s_nop 0
	v_add_u32_e32 v201, -1, v200
	v_add_u32_e32 v202, 1, v200
	v_fma_f32 v203, -v201, v200, v198
	v_fma_f32 v204, -v202, v200, v198
	v_cmp_ge_f32_e64 s[8:9], 0, v203
	s_nop 1
	v_cndmask_b32_e64 v200, v200, v201, s[8:9]
	v_cmp_lt_f32_e64 s[8:9], 0, v204
	s_nop 1
	v_cndmask_b32_e64 v200, v200, v202, s[8:9]
	v_mul_f32_e32 v201, 0x37800000, v200
	v_cndmask_b32_e32 v200, v200, v201, vcc
	v_cmp_class_f32_e32 vcc, v198, v170
	s_nop 1
	v_cndmask_b32_e32 v198, v200, v198, vcc
	v_div_scale_f32 v202, s[8:9], v198, v198, 1.0
	v_rcp_f32_e32 v203, v202
	v_div_scale_f32 v200, vcc, 1.0, v198, 1.0
	v_fma_f32 v201, -v202, v203, 1.0
	v_fmac_f32_e32 v203, v201, v203
	v_mul_f32_e32 v201, v200, v203
	v_fma_f32 v204, -v202, v201, v200
	v_fmac_f32_e32 v201, v204, v203
	v_fma_f32 v200, -v202, v201, v200
	v_div_fmas_f32 v200, v200, v203, v201
	v_div_fixup_f32 v206, v200, v198, 1.0
	v_pk_mul_f32 v[28:29], v[28:29], v[206:207] op_sel_hi:[1,0]
	v_pk_mul_f32 v[30:31], v[30:31], v[206:207] op_sel_hi:[1,0]
	v_pk_mul_f32 v[28:29], v[176:177], v[28:29]
	v_pk_mul_f32 v[30:31], v[178:179], v[30:31]
	v_pk_mul_f32 v[24:25], v[24:25], v[206:207] op_sel_hi:[1,0]
	v_pk_mul_f32 v[26:27], v[26:27], v[206:207] op_sel_hi:[1,0]
	v_pk_mul_f32 v[24:25], v[180:181], v[24:25]
	v_pk_mul_f32 v[26:27], v[182:183], v[26:27]
	v_pk_mul_f32 v[20:21], v[20:21], v[206:207] op_sel_hi:[1,0]
	v_pk_mul_f32 v[22:23], v[22:23], v[206:207] op_sel_hi:[1,0]
	v_pk_mul_f32 v[20:21], v[184:185], v[20:21]
	v_pk_mul_f32 v[22:23], v[186:187], v[22:23]
	v_pk_mul_f32 v[16:17], v[16:17], v[206:207] op_sel_hi:[1,0]
	v_pk_mul_f32 v[18:19], v[18:19], v[206:207] op_sel_hi:[1,0]
	v_pk_mul_f32 v[16:17], v[188:189], v[16:17]
	v_pk_mul_f32 v[18:19], v[190:191], v[18:19]
	ds_write_b128 v171, v[28:31]
	ds_write_b128 v171, v[24:27] offset:64
	ds_read_b128 v[28:31], v172
	ds_read_b128 v[24:27], v172 offset:1152
	ds_write_b128 v171, v[20:23]
	ds_write_b128 v171, v[16:19] offset:64
	ds_read_b128 v[20:23], v172
	ds_read_b128 v[16:19], v172 offset:1152
	s_add_u32 s100, s14, 0xa0000
	s_addc_u32 s101, s15, 0
	s_add_u32 s44, s14, 0xa8000
	s_addc_u32 s45, s15, 0
	s_waitcnt lgkmcnt(4)
	global_store_dwordx4 v142, v[28:31], s[100:101] nt
	global_store_dwordx4 v142, v[24:27], s[44:45] nt
	s_waitcnt lgkmcnt(0)
	global_store_dwordx4 v142, v[20:23], s[100:101] offset:512 nt
	global_store_dwordx4 v142, v[16:19], s[44:45] offset:512 nt
	v_fmamk_f32 v199, v199, 0x3a800000, v169
	v_mul_f32_e32 v200, 0x4f800000, v199
	v_cmp_gt_f32_e32 vcc, s68, v199
	s_nop 1
	v_cndmask_b32_e32 v199, v199, v200, vcc
	v_sqrt_f32_e32 v200, v199
	s_nop 0
	v_add_u32_e32 v201, -1, v200
	v_add_u32_e32 v202, 1, v200
	v_fma_f32 v203, -v201, v200, v199
	v_fma_f32 v204, -v202, v200, v199
	v_cmp_ge_f32_e64 s[8:9], 0, v203
	s_nop 1
	v_cndmask_b32_e64 v200, v200, v201, s[8:9]
	v_cmp_lt_f32_e64 s[8:9], 0, v204
	s_nop 1
	v_cndmask_b32_e64 v200, v200, v202, s[8:9]
	v_mul_f32_e32 v201, 0x37800000, v200
	v_cndmask_b32_e32 v200, v200, v201, vcc
	v_cmp_class_f32_e32 vcc, v199, v170
	s_nop 1
	v_cndmask_b32_e32 v199, v200, v199, vcc
	v_div_scale_f32 v202, s[8:9], v199, v199, 1.0
	v_rcp_f32_e32 v203, v202
	v_div_scale_f32 v200, vcc, 1.0, v199, 1.0
	v_fma_f32 v201, -v202, v203, 1.0
	v_fmac_f32_e32 v203, v201, v203
	v_mul_f32_e32 v201, v200, v203
	v_fma_f32 v204, -v202, v201, v200
	v_fmac_f32_e32 v201, v204, v203
	v_fma_f32 v200, -v202, v201, v200
	v_div_fmas_f32 v200, v200, v203, v201
	v_div_fixup_f32 v206, v200, v199, 1.0
	v_pk_mul_f32 v[12:13], v[12:13], v[206:207] op_sel_hi:[1,0]
	v_pk_mul_f32 v[14:15], v[14:15], v[206:207] op_sel_hi:[1,0]
	v_pk_mul_f32 v[12:13], v[176:177], v[12:13]
	v_pk_mul_f32 v[14:15], v[178:179], v[14:15]
	v_pk_mul_f32 v[8:9], v[8:9], v[206:207] op_sel_hi:[1,0]
	v_pk_mul_f32 v[10:11], v[10:11], v[206:207] op_sel_hi:[1,0]
	v_pk_mul_f32 v[8:9], v[180:181], v[8:9]
	v_pk_mul_f32 v[10:11], v[182:183], v[10:11]
	v_pk_mul_f32 v[4:5], v[4:5], v[206:207] op_sel_hi:[1,0]
	v_pk_mul_f32 v[6:7], v[6:7], v[206:207] op_sel_hi:[1,0]
	v_pk_mul_f32 v[4:5], v[184:185], v[4:5]
	v_pk_mul_f32 v[6:7], v[186:187], v[6:7]
	v_pk_mul_f32 v[0:1], v[0:1], v[206:207] op_sel_hi:[1,0]
	v_pk_mul_f32 v[2:3], v[2:3], v[206:207] op_sel_hi:[1,0]
	v_pk_mul_f32 v[0:1], v[188:189], v[0:1]
	v_pk_mul_f32 v[2:3], v[190:191], v[2:3]
	ds_write_b128 v171, v[12:15]
	ds_write_b128 v171, v[8:11] offset:64
	ds_read_b128 v[12:15], v172
	ds_read_b128 v[8:11], v172 offset:1152
	ds_write_b128 v171, v[4:7]
	ds_write_b128 v171, v[0:3] offset:64
	ds_read_b128 v[4:7], v172
	ds_read_b128 v[0:3], v172 offset:1152
	s_add_u32 s100, s14, 0xb0000
	s_addc_u32 s101, s15, 0
	s_add_u32 s44, s14, 0xb8000
	s_addc_u32 s45, s15, 0
	s_waitcnt lgkmcnt(4)
	global_store_dwordx4 v142, v[12:15], s[100:101] nt
	global_store_dwordx4 v142, v[8:11], s[44:45] nt
	s_waitcnt lgkmcnt(0)
	global_store_dwordx4 v142, v[4:7], s[100:101] offset:512 nt
	global_store_dwordx4 v142, v[0:3], s[44:45] offset:512 nt
	s_andn2_b64 vcc, exec, s[6:7]
	s_mov_b64 s[6:7], -1
	s_mov_b32 s32, 40
	s_cbranch_vccnz .LBB0_477
	s_andn2_b64 vcc, exec, s[20:21]
	s_cbranch_vccnz .LBB0_476
	s_barrier
	s_branch .LBB0_476
